# 7 local seams + S3,S6,S13 as group-rendezvous without L2 writeback (old-layout ACT buffers stored write-through sc1) + early L1 invalidate
# speedup vs baseline: 1.0091x; 1.0091x over previous
; #define PG8_LAS __attribute__((address_space(3)))
; __device__ __forceinline__ unsigned pk_bf16(float lo, float hi) { typedef __bf16 b2_t __attribute__((ext_vector_type(2))); f32x2 v = {lo, hi}; b2_t b = __builtin_convertvector(v, b2_t); return __builtin_bit_cast(unsigned, b); }
;     __device__ __forceinline__ void operator()(const f32x4 (&acc)[2][2][4][2], const Unit& u, int wr, int wc, int fr, int fq, PG8_LAS unsigned char* lds, int wid) const {
;         const int row0 = u.pm * BM + wr * 64 + fr, col0 = u.pn * HALF + wc * 32 + 8 * fq;
; #pragma unroll
;         for (int ai = 0; ai < 2; ++ai)
; #pragma unroll
;             for (int m = 0; m < 4; ++m) {
;                 bf16_t* p = H + (size_t)(row0 + ai * HALF + m * 16) * ldh + col0;
;                 const float rstd = __builtin_amdgcn_rsqf(*(const PG8_LAS float*)(lds + PRE_SLOT + wid * 512 + (m & 1) * 256 + (fr + 16 * ((ai * 4 + m) >> 1)) * 4) * (1.0f / 1024.0f) + 1e-6f);
;                 const float c1 = -1.44269504089f * rstd, r2 = rstd * rstd;
;                 f32x2 hh[4];
; #pragma unroll
;                 for (int q = 0; q < 4; ++q) {
;                     const f32x2 ag = {acc[ai][0][m][q >> 1][2 * (q & 1)], acc[ai][0][m][q >> 1][2 * (q & 1) + 1]};
;                     const f32x2 au = {acc[ai][1][m][q >> 1][2 * (q & 1)], acc[ai][1][m][q >> 1][2 * (q & 1) + 1]};
;                     const f32x2 t = ag * c1;
;                     f32x2 e; e.x = __builtin_amdgcn_exp2f(t.x); e.y = __builtin_amdgcn_exp2f(t.y);
;                     const f32x2 d = e + 1.0f;
;                     f32x2 r; r.x = __builtin_amdgcn_rcpf(d.x); r.y = __builtin_amdgcn_rcpf(d.y);
;                     hh[q] = (ag * au) * (r * r2);
;                 }
;                 u32x4 w; w.x = pk_bf16(hh[0].x, hh[0].y); w.y = pk_bf16(hh[1].x, hh[1].y); w.z = pk_bf16(hh[2].x, hh[2].y); w.w = pk_bf16(hh[3].x, hh[3].y);
;                 *(u32x4*)p = w;
;             }
;     }
.LBB0_110:
	v_add_u32_e32 v163, s41, v145
	ds_read2_b32 v[154:155], v163 offset1:16
	v_lshl_or_b32 v156, s21, 7, v147
	v_lshl_add_u32 v0, s20, 8, v144
	v_ashrrev_i32_e32 v157, 31, v156
	v_pk_mul_f32 v[64:65], v[68:69], v[64:65]
	s_waitcnt lgkmcnt(0)
	v_fmamk_f32 v2, v154, 0x3a800000, v148
	v_rsq_f32_e32 v162, v2
	v_mov_b64_e32 v[2:3], s[50:51]
	v_mad_i64_i32 v[160:161], s[20:21], v0, s65, v[2:3]
	v_mul_f32_e32 v154, 0xbfb8aa3b, v162
	v_pk_mul_f32 v[158:159], v[124:125], v[154:155] op_sel_hi:[1,0]
	v_pk_mul_f32 v[164:165], v[126:127], v[154:155] op_sel_hi:[1,0]
	v_exp_f32_e32 v158, v158
	v_exp_f32_e32 v159, v159
	v_exp_f32_e32 v164, v164
	v_exp_f32_e32 v165, v165
	v_mul_f32_e32 v162, v162, v162
	v_pk_add_f32 v[158:159], v[158:159], 1.0 op_sel_hi:[1,0]
	v_pk_mul_f32 v[126:127], v[126:127], v[130:131]
	v_rcp_f32_e32 v158, v158
	v_rcp_f32_e32 v159, v159
	v_pk_add_f32 v[130:131], v[164:165], 1.0 op_sel_hi:[1,0]
	v_pk_mul_f32 v[124:125], v[124:125], v[128:129]
	v_rcp_f32_e32 v130, v130
	v_pk_mul_f32 v[128:129], v[162:163], v[158:159] op_sel_hi:[0,1]
	v_rcp_f32_e32 v131, v131
	v_pk_mul_f32 v[158:159], v[116:117], v[154:155] op_sel_hi:[1,0]
	v_pk_mul_f32 v[124:125], v[124:125], v[128:129]
	v_exp_f32_e32 v158, v158
	v_exp_f32_e32 v159, v159
	v_pk_mul_f32 v[128:129], v[162:163], v[130:131] op_sel_hi:[0,1]
	v_pk_mul_f32 v[126:127], v[126:127], v[128:129]
	v_pk_mul_f32 v[130:131], v[118:119], v[154:155] op_sel_hi:[1,0]
	v_pk_add_f32 v[128:129], v[158:159], 1.0 op_sel_hi:[1,0]
	v_exp_f32_e32 v130, v130
	v_exp_f32_e32 v131, v131
	v_rcp_f32_e32 v128, v128
	v_rcp_f32_e32 v129, v129
	v_pk_mul_f32 v[118:119], v[118:119], v[122:123]
	v_pk_add_f32 v[122:123], v[130:131], 1.0 op_sel_hi:[1,0]
	v_pk_mul_f32 v[116:117], v[116:117], v[120:121]
	v_pk_mul_f32 v[120:121], v[162:163], v[128:129] op_sel_hi:[0,1]
	ds_read2_b32 v[128:129], v163 offset0:64 offset1:80
	v_rcp_f32_e32 v122, v122
	v_rcp_f32_e32 v123, v123
	v_pk_mul_f32 v[120:121], v[116:117], v[120:121]
	v_pk_mul_f32 v[66:67], v[70:71], v[66:67]
	v_cvt_pk_bf16_f32 v120, v120, v121
	v_pk_mul_f32 v[116:117], v[162:163], v[122:123] op_sel_hi:[0,1]
	s_waitcnt lgkmcnt(0)
	v_fmamk_f32 v121, v128, 0x3a800000, v148
	v_pk_mul_f32 v[122:123], v[118:119], v[116:117]
	v_cvt_pk_bf16_f32 v118, v124, v125
	v_rsq_f32_e32 v124, v121
	v_lshlrev_b64 v[116:117], 1, v[156:157]
	v_lshl_add_u64 v[130:131], v[160:161], 0, v[116:117]
	v_cvt_pk_bf16_f32 v119, v126, v127
	v_cvt_pk_bf16_f32 v121, v122, v123
	global_store_dwordx4 v[130:131], v[118:121], off sc1
	v_pk_mul_f32 v[54:55], v[58:59], v[54:55]
	v_pk_mul_f32 v[52:53], v[56:57], v[52:53]
	v_or_b32_e32 v119, 16, v0
	v_mul_f32_e32 v118, 0xbfb8aa3b, v124
	v_pk_mul_f32 v[120:121], v[108:109], v[118:119] op_sel_hi:[1,0]
	v_pk_mul_f32 v[126:127], v[110:111], v[118:119] op_sel_hi:[1,0]
	v_exp_f32_e32 v120, v120
	v_exp_f32_e32 v121, v121
	v_exp_f32_e32 v126, v126
	v_exp_f32_e32 v127, v127
	v_pk_mul_f32 v[110:111], v[110:111], v[114:115]
	v_pk_add_f32 v[120:121], v[120:121], 1.0 op_sel_hi:[1,0]
	v_mul_f32_e32 v124, v124, v124
	v_rcp_f32_e32 v120, v120
	v_rcp_f32_e32 v121, v121
	v_pk_add_f32 v[114:115], v[126:127], 1.0 op_sel_hi:[1,0]
	v_pk_mul_f32 v[108:109], v[108:109], v[112:113]
	v_rcp_f32_e32 v114, v114
	v_rcp_f32_e32 v115, v115
	v_pk_mul_f32 v[112:113], v[124:125], v[120:121] op_sel_hi:[0,1]
	v_pk_mul_f32 v[120:121], v[100:101], v[118:119] op_sel_hi:[1,0]
	v_pk_mul_f32 v[108:109], v[108:109], v[112:113]
	v_exp_f32_e32 v120, v120
	v_exp_f32_e32 v121, v121
	v_pk_mul_f32 v[112:113], v[124:125], v[114:115] op_sel_hi:[0,1]
	v_pk_mul_f32 v[114:115], v[102:103], v[118:119] op_sel_hi:[1,0]
	v_pk_mul_f32 v[110:111], v[110:111], v[112:113]
	v_exp_f32_e32 v114, v114
	v_exp_f32_e32 v115, v115
	v_pk_add_f32 v[112:113], v[120:121], 1.0 op_sel_hi:[1,0]
	v_pk_mul_f32 v[102:103], v[102:103], v[106:107]
	v_rcp_f32_e32 v112, v112
	v_rcp_f32_e32 v113, v113
	v_pk_add_f32 v[106:107], v[114:115], 1.0 op_sel_hi:[1,0]
	v_pk_mul_f32 v[100:101], v[100:101], v[104:105]
	v_rcp_f32_e32 v106, v106
	v_rcp_f32_e32 v107, v107
	v_pk_mul_f32 v[104:105], v[124:125], v[112:113] op_sel_hi:[0,1]
	v_pk_mul_f32 v[104:105], v[100:101], v[104:105]
	v_mad_i64_i32 v[122:123], s[20:21], v119, s65, v[2:3]
	v_pk_mul_f32 v[100:101], v[124:125], v[106:107] op_sel_hi:[0,1]
	v_pk_mul_f32 v[106:107], v[102:103], v[100:101]
	v_fmamk_f32 v103, v155, 0x3a800000, v148
	v_cvt_pk_bf16_f32 v100, v108, v109
	v_rsq_f32_e32 v108, v103
	v_lshl_add_u64 v[112:113], v[122:123], 0, v[116:117]
	v_cvt_pk_bf16_f32 v101, v110, v111
	v_cvt_pk_bf16_f32 v102, v104, v105
	v_cvt_pk_bf16_f32 v103, v106, v107
	global_store_dwordx4 v[112:113], v[100:103], off sc1
	v_mul_f32_e32 v106, v108, v108
	v_pk_mul_f32 v[46:47], v[50:51], v[46:47]
	v_or_b32_e32 v101, 32, v0
	v_mul_f32_e32 v100, 0xbfb8aa3b, v108
	v_pk_mul_f32 v[102:103], v[92:93], v[100:101] op_sel_hi:[1,0]
	v_pk_mul_f32 v[108:109], v[94:95], v[100:101] op_sel_hi:[1,0]
	v_exp_f32_e32 v102, v102
	v_exp_f32_e32 v103, v103
	v_exp_f32_e32 v108, v108
	v_exp_f32_e32 v109, v109
	v_pk_mul_f32 v[94:95], v[94:95], v[98:99]
	v_pk_add_f32 v[102:103], v[102:103], 1.0 op_sel_hi:[1,0]
	v_pk_mul_f32 v[92:93], v[92:93], v[96:97]
	v_rcp_f32_e32 v102, v102
	v_rcp_f32_e32 v103, v103
	v_pk_add_f32 v[98:99], v[108:109], 1.0 op_sel_hi:[1,0]
	v_mad_i64_i32 v[104:105], s[20:21], v101, s65, v[2:3]
	v_rcp_f32_e32 v98, v98
	v_rcp_f32_e32 v99, v99
	v_pk_mul_f32 v[96:97], v[106:107], v[102:103] op_sel_hi:[0,1]
	v_pk_mul_f32 v[102:103], v[84:85], v[100:101] op_sel_hi:[1,0]
	v_pk_mul_f32 v[92:93], v[92:93], v[96:97]
	v_exp_f32_e32 v102, v102
	v_exp_f32_e32 v103, v103
	v_pk_mul_f32 v[96:97], v[106:107], v[98:99] op_sel_hi:[0,1]
; #define PG8_LAS __attribute__((address_space(3)))
; __device__ __forceinline__ unsigned pk_bf16(float lo, float hi) { typedef __bf16 b2_t __attribute__((ext_vector_type(2))); f32x2 v = {lo, hi}; b2_t b = __builtin_convertvector(v, b2_t); return __builtin_bit_cast(unsigned, b); }
;     __device__ __forceinline__ void operator()(const f32x4 (&acc)[2][2][4][2], const Unit& u, int wr, int wc, int fr, int fq, PG8_LAS unsigned char* lds, int wid) const {
;     ...
;                 const float rstd = __builtin_amdgcn_rsqf(*(const PG8_LAS float*)(lds + PRE_SLOT + wid * 512 + (m & 1) * 256 + (fr + 16 * ((ai * 4 + m) >> 1)) * 4) * (1.0f / 1024.0f) + 1e-6f);
;                 const float c1 = -1.44269504089f * rstd, r2 = rstd * rstd;
;                 f32x2 hh[4];
; #pragma unroll
;                 for (int q = 0; q < 4; ++q) {
;                     const f32x2 ag = {acc[ai][0][m][q >> 1][2 * (q & 1)], acc[ai][0][m][q >> 1][2 * (q & 1) + 1]};
;                     const f32x2 au = {acc[ai][1][m][q >> 1][2 * (q & 1)], acc[ai][1][m][q >> 1][2 * (q & 1) + 1]};
;                     const f32x2 t = ag * c1;
;                     f32x2 e; e.x = __builtin_amdgcn_exp2f(t.x); e.y = __builtin_amdgcn_exp2f(t.y);
;                     const f32x2 d = e + 1.0f;
;                     f32x2 r; r.x = __builtin_amdgcn_rcpf(d.x); r.y = __builtin_amdgcn_rcpf(d.y);
;                     hh[q] = (ag * au) * (r * r2);
;                 }
;                 u32x4 w; w.x = pk_bf16(hh[0].x, hh[0].y); w.y = pk_bf16(hh[1].x, hh[1].y); w.z = pk_bf16(hh[2].x, hh[2].y); w.w = pk_bf16(hh[3].x, hh[3].y);
;                 *(u32x4*)p = w;
	v_pk_mul_f32 v[98:99], v[86:87], v[100:101] op_sel_hi:[1,0]
	v_pk_mul_f32 v[94:95], v[94:95], v[96:97]
	v_exp_f32_e32 v98, v98
	v_exp_f32_e32 v99, v99
	v_pk_add_f32 v[96:97], v[102:103], 1.0 op_sel_hi:[1,0]
	v_pk_mul_f32 v[86:87], v[86:87], v[90:91]
	v_rcp_f32_e32 v96, v96
	v_rcp_f32_e32 v97, v97
	v_pk_add_f32 v[90:91], v[98:99], 1.0 op_sel_hi:[1,0]
	v_pk_mul_f32 v[84:85], v[84:85], v[88:89]
	v_rcp_f32_e32 v90, v90
	v_rcp_f32_e32 v91, v91
	v_pk_mul_f32 v[88:89], v[106:107], v[96:97] op_sel_hi:[0,1]
	v_pk_mul_f32 v[88:89], v[84:85], v[88:89]
	v_lshl_add_u64 v[96:97], v[104:105], 0, v[116:117]
	v_pk_mul_f32 v[84:85], v[106:107], v[90:91] op_sel_hi:[0,1]
	v_pk_mul_f32 v[90:91], v[86:87], v[84:85]
	v_fmamk_f32 v87, v129, 0x3a800000, v148
	v_cvt_pk_bf16_f32 v84, v92, v93
	v_rsq_f32_e32 v92, v87
	v_cvt_pk_bf16_f32 v85, v94, v95
	v_cvt_pk_bf16_f32 v86, v88, v89
	v_cvt_pk_bf16_f32 v87, v90, v91
	global_store_dwordx4 v[96:97], v[84:87], off sc1
	v_mul_f32_e32 v90, v92, v92
	v_pk_mul_f32 v[44:45], v[48:49], v[44:45]
	v_or_b32_e32 v85, 48, v0
	v_mul_f32_e32 v84, 0xbfb8aa3b, v92
	v_pk_mul_f32 v[86:87], v[76:77], v[84:85] op_sel_hi:[1,0]
	v_pk_mul_f32 v[92:93], v[78:79], v[84:85] op_sel_hi:[1,0]
	v_exp_f32_e32 v86, v86
	v_exp_f32_e32 v87, v87
	v_exp_f32_e32 v92, v92
	v_exp_f32_e32 v93, v93
	v_pk_mul_f32 v[78:79], v[78:79], v[82:83]
	v_pk_add_f32 v[86:87], v[86:87], 1.0 op_sel_hi:[1,0]
	v_pk_mul_f32 v[76:77], v[76:77], v[80:81]
	v_rcp_f32_e32 v86, v86
	v_rcp_f32_e32 v87, v87
	v_pk_add_f32 v[82:83], v[92:93], 1.0 op_sel_hi:[1,0]
	v_mad_i64_i32 v[88:89], s[20:21], v85, s65, v[2:3]
	v_pk_mul_f32 v[80:81], v[90:91], v[86:87] op_sel_hi:[0,1]
	v_rcp_f32_e32 v82, v82
	v_rcp_f32_e32 v83, v83
	v_pk_mul_f32 v[86:87], v[60:61], v[84:85] op_sel_hi:[1,0]
	v_pk_mul_f32 v[76:77], v[76:77], v[80:81]
	v_exp_f32_e32 v86, v86
	v_exp_f32_e32 v87, v87
	v_pk_mul_f32 v[80:81], v[90:91], v[82:83] op_sel_hi:[0,1]
	v_pk_mul_f32 v[82:83], v[62:63], v[84:85] op_sel_hi:[1,0]
	v_pk_mul_f32 v[78:79], v[78:79], v[80:81]
	v_pk_add_f32 v[80:81], v[86:87], 1.0 op_sel_hi:[1,0]
	v_exp_f32_e32 v82, v82
	v_exp_f32_e32 v83, v83
	v_rcp_f32_e32 v80, v80
	v_rcp_f32_e32 v81, v81
	v_pk_mul_f32 v[62:63], v[62:63], v[74:75]
	v_pk_add_f32 v[74:75], v[82:83], 1.0 op_sel_hi:[1,0]
	v_pk_mul_f32 v[60:61], v[60:61], v[72:73]
	v_rcp_f32_e32 v74, v74
	v_rcp_f32_e32 v75, v75
	v_pk_mul_f32 v[72:73], v[90:91], v[80:81] op_sel_hi:[0,1]
	ds_read2_b32 v[80:81], v163 offset0:32 offset1:48
	v_pk_mul_f32 v[72:73], v[60:61], v[72:73]
	v_pk_mul_f32 v[60:61], v[90:91], v[74:75] op_sel_hi:[0,1]
	v_pk_mul_f32 v[74:75], v[62:63], v[60:61]
	v_cvt_pk_bf16_f32 v60, v76, v77
	s_waitcnt lgkmcnt(0)
	v_fmamk_f32 v63, v80, 0x3a800000, v148
	v_rsq_f32_e32 v76, v63
	v_lshl_add_u64 v[82:83], v[88:89], 0, v[116:117]
	v_cvt_pk_bf16_f32 v61, v78, v79
	v_cvt_pk_bf16_f32 v62, v72, v73
	v_cvt_pk_bf16_f32 v63, v74, v75
	global_store_dwordx4 v[82:83], v[60:63], off sc1
	v_mul_f32_e32 v74, v76, v76
	v_pk_mul_f32 v[38:39], v[42:43], v[38:39]
	v_add_u32_e32 v61, 0x80, v0
	v_mul_f32_e32 v60, 0xbfb8aa3b, v76
	v_pk_mul_f32 v[62:63], v[68:69], v[60:61] op_sel_hi:[1,0]
	v_pk_mul_f32 v[76:77], v[70:71], v[60:61] op_sel_hi:[1,0]
	v_exp_f32_e32 v62, v62
	v_exp_f32_e32 v63, v63
	v_exp_f32_e32 v76, v76
	v_exp_f32_e32 v77, v77
	v_pk_mul_f32 v[70:71], v[56:57], v[60:61] op_sel_hi:[1,0]
	v_pk_add_f32 v[62:63], v[62:63], 1.0 op_sel_hi:[1,0]
	v_mad_i64_i32 v[72:73], s[20:21], v61, s65, v[2:3]
	v_rcp_f32_e32 v62, v62
	v_rcp_f32_e32 v63, v63
	v_pk_add_f32 v[68:69], v[76:77], 1.0 op_sel_hi:[1,0]
	v_exp_f32_e32 v70, v70
	v_rcp_f32_e32 v68, v68
	v_rcp_f32_e32 v69, v69
	v_exp_f32_e32 v71, v71
	v_pk_mul_f32 v[60:61], v[58:59], v[60:61] op_sel_hi:[1,0]
	v_pk_mul_f32 v[62:63], v[74:75], v[62:63] op_sel_hi:[0,1]
	v_exp_f32_e32 v60, v60
	v_exp_f32_e32 v61, v61
	v_pk_mul_f32 v[62:63], v[64:65], v[62:63]
	v_pk_mul_f32 v[64:65], v[74:75], v[68:69] op_sel_hi:[0,1]
	v_pk_mul_f32 v[64:65], v[66:67], v[64:65]
	v_pk_add_f32 v[66:67], v[70:71], 1.0 op_sel_hi:[1,0]
	v_pk_add_f32 v[58:59], v[60:61], 1.0 op_sel_hi:[1,0]
	v_rcp_f32_e32 v66, v66
	v_rcp_f32_e32 v67, v67
	v_rcp_f32_e32 v58, v58
	v_rcp_f32_e32 v59, v59
	ds_read2_b32 v[60:61], v163 offset0:96 offset1:112
	v_pk_mul_f32 v[56:57], v[74:75], v[66:67] op_sel_hi:[0,1]
	v_pk_mul_f32 v[56:57], v[52:53], v[56:57]
	v_pk_mul_f32 v[52:53], v[74:75], v[58:59] op_sel_hi:[0,1]
	v_pk_mul_f32 v[58:59], v[54:55], v[52:53]
	s_waitcnt lgkmcnt(0)
; #define PG8_LAS __attribute__((address_space(3)))
; __device__ __forceinline__ unsigned pk_bf16(float lo, float hi) { typedef __bf16 b2_t __attribute__((ext_vector_type(2))); f32x2 v = {lo, hi}; b2_t b = __builtin_convertvector(v, b2_t); return __builtin_bit_cast(unsigned, b); }
;     __device__ __forceinline__ void operator()(const f32x4 (&acc)[2][2][4][2], const Unit& u, int wr, int wc, int fr, int fq, PG8_LAS unsigned char* lds, int wid) const {
;     ...
;                 const float rstd = __builtin_amdgcn_rsqf(*(const PG8_LAS float*)(lds + PRE_SLOT + wid * 512 + (m & 1) * 256 + (fr + 16 * ((ai * 4 + m) >> 1)) * 4) * (1.0f / 1024.0f) + 1e-6f);
;                 const float c1 = -1.44269504089f * rstd, r2 = rstd * rstd;
;                 f32x2 hh[4];
; #pragma unroll
;                 for (int q = 0; q < 4; ++q) {
;                     const f32x2 ag = {acc[ai][0][m][q >> 1][2 * (q & 1)], acc[ai][0][m][q >> 1][2 * (q & 1) + 1]};
;                     const f32x2 au = {acc[ai][1][m][q >> 1][2 * (q & 1)], acc[ai][1][m][q >> 1][2 * (q & 1) + 1]};
;                     const f32x2 t = ag * c1;
;                     f32x2 e; e.x = __builtin_amdgcn_exp2f(t.x); e.y = __builtin_amdgcn_exp2f(t.y);
;                     const f32x2 d = e + 1.0f;
;                     f32x2 r; r.x = __builtin_amdgcn_rcpf(d.x); r.y = __builtin_amdgcn_rcpf(d.y);
;                     hh[q] = (ag * au) * (r * r2);
;                 }
;                 u32x4 w; w.x = pk_bf16(hh[0].x, hh[0].y); w.y = pk_bf16(hh[1].x, hh[1].y); w.z = pk_bf16(hh[2].x, hh[2].y); w.w = pk_bf16(hh[3].x, hh[3].y);
;                 *(u32x4*)p = w;
;             }
;     }
	v_fmamk_f32 v55, v60, 0x3a800000, v148
	v_rsq_f32_e32 v60, v55
	v_lshl_add_u64 v[66:67], v[72:73], 0, v[116:117]
	v_cvt_pk_bf16_f32 v52, v62, v63
	v_cvt_pk_bf16_f32 v53, v64, v65
	v_cvt_pk_bf16_f32 v54, v56, v57
	v_cvt_pk_bf16_f32 v55, v58, v59
	global_store_dwordx4 v[66:67], v[52:55], off sc1
	v_mul_f32_e32 v58, v60, v60
	v_pk_mul_f32 v[36:37], v[40:41], v[36:37]
	v_add_u32_e32 v53, 0x90, v0
	v_mul_f32_e32 v52, 0xbfb8aa3b, v60
	v_pk_mul_f32 v[54:55], v[48:49], v[52:53] op_sel_hi:[1,0]
	v_pk_mul_f32 v[62:63], v[50:51], v[52:53] op_sel_hi:[1,0]
	v_exp_f32_e32 v54, v54
	v_exp_f32_e32 v55, v55
	v_exp_f32_e32 v62, v62
	v_exp_f32_e32 v63, v63
	v_mad_i64_i32 v[56:57], s[20:21], v53, s65, v[2:3]
	v_pk_add_f32 v[54:55], v[54:55], 1.0 op_sel_hi:[1,0]
	v_pk_add_f32 v[50:51], v[62:63], 1.0 op_sel_hi:[1,0]
	v_rcp_f32_e32 v54, v54
	v_rcp_f32_e32 v55, v55
	v_rcp_f32_e32 v50, v50
	v_rcp_f32_e32 v51, v51
	v_pk_mul_f32 v[30:31], v[34:35], v[30:31]
	v_pk_mul_f32 v[48:49], v[58:59], v[54:55] op_sel_hi:[0,1]
	v_pk_mul_f32 v[54:55], v[40:41], v[52:53] op_sel_hi:[1,0]
	v_pk_mul_f32 v[44:45], v[44:45], v[48:49]
	v_exp_f32_e32 v54, v54
	v_exp_f32_e32 v55, v55
	v_pk_mul_f32 v[48:49], v[58:59], v[50:51] op_sel_hi:[0,1]
	v_pk_mul_f32 v[50:51], v[42:43], v[52:53] op_sel_hi:[1,0]
	v_pk_mul_f32 v[46:47], v[46:47], v[48:49]
	v_exp_f32_e32 v50, v50
	v_exp_f32_e32 v51, v51
	v_pk_add_f32 v[48:49], v[54:55], 1.0 op_sel_hi:[1,0]
	v_pk_mul_f32 v[28:29], v[32:33], v[28:29]
	v_rcp_f32_e32 v48, v48
	v_rcp_f32_e32 v49, v49
	v_pk_add_f32 v[42:43], v[50:51], 1.0 op_sel_hi:[1,0]
	v_pk_mul_f32 v[22:23], v[26:27], v[22:23]
	v_rcp_f32_e32 v42, v42
	v_rcp_f32_e32 v43, v43
	v_pk_mul_f32 v[40:41], v[58:59], v[48:49] op_sel_hi:[0,1]
	v_pk_mul_f32 v[40:41], v[36:37], v[40:41]
	v_lshl_add_u64 v[48:49], v[56:57], 0, v[116:117]
	v_pk_mul_f32 v[36:37], v[58:59], v[42:43] op_sel_hi:[0,1]
	v_pk_mul_f32 v[42:43], v[38:39], v[36:37]
	v_fmamk_f32 v39, v81, 0x3a800000, v148
	v_cvt_pk_bf16_f32 v36, v44, v45
	v_rsq_f32_e32 v44, v39
	v_cvt_pk_bf16_f32 v37, v46, v47
	v_cvt_pk_bf16_f32 v38, v40, v41
	v_cvt_pk_bf16_f32 v39, v42, v43
	global_store_dwordx4 v[48:49], v[36:39], off sc1
	v_mul_f32_e32 v42, v44, v44
	v_pk_mul_f32 v[20:21], v[24:25], v[20:21]
	v_add_u32_e32 v37, 0xa0, v0
	v_mul_f32_e32 v36, 0xbfb8aa3b, v44
	v_pk_mul_f32 v[38:39], v[32:33], v[36:37] op_sel_hi:[1,0]
	v_pk_mul_f32 v[44:45], v[34:35], v[36:37] op_sel_hi:[1,0]
	v_exp_f32_e32 v38, v38
	v_exp_f32_e32 v39, v39
	v_exp_f32_e32 v44, v44
	v_exp_f32_e32 v45, v45
	v_mad_i64_i32 v[40:41], s[20:21], v37, s65, v[2:3]
	v_pk_add_f32 v[38:39], v[38:39], 1.0 op_sel_hi:[1,0]
	v_pk_add_f32 v[34:35], v[44:45], 1.0 op_sel_hi:[1,0]
	v_rcp_f32_e32 v38, v38
	v_rcp_f32_e32 v39, v39
	v_rcp_f32_e32 v34, v34
	v_rcp_f32_e32 v35, v35
	v_pk_mul_f32 v[14:15], v[18:19], v[14:15]
	v_pk_mul_f32 v[32:33], v[42:43], v[38:39] op_sel_hi:[0,1]
	v_pk_mul_f32 v[38:39], v[24:25], v[36:37] op_sel_hi:[1,0]
	v_pk_mul_f32 v[28:29], v[28:29], v[32:33]
	v_exp_f32_e32 v38, v38
	v_exp_f32_e32 v39, v39
	v_pk_mul_f32 v[32:33], v[42:43], v[34:35] op_sel_hi:[0,1]
	v_pk_mul_f32 v[34:35], v[26:27], v[36:37] op_sel_hi:[1,0]
	v_pk_mul_f32 v[30:31], v[30:31], v[32:33]
	v_exp_f32_e32 v34, v34
	v_exp_f32_e32 v35, v35
	v_pk_add_f32 v[32:33], v[38:39], 1.0 op_sel_hi:[1,0]
	v_pk_mul_f32 v[12:13], v[16:17], v[12:13]
	v_rcp_f32_e32 v32, v32
	v_rcp_f32_e32 v33, v33
	v_pk_add_f32 v[26:27], v[34:35], 1.0 op_sel_hi:[1,0]
	s_andn2_b64 vcc, exec, s[2:3]
	v_rcp_f32_e32 v26, v26
	v_rcp_f32_e32 v27, v27
	v_pk_mul_f32 v[24:25], v[42:43], v[32:33] op_sel_hi:[0,1]
	v_pk_mul_f32 v[24:25], v[20:21], v[24:25]
	v_lshl_add_u64 v[32:33], v[40:41], 0, v[116:117]
	v_pk_mul_f32 v[20:21], v[42:43], v[26:27] op_sel_hi:[0,1]
	v_pk_mul_f32 v[26:27], v[22:23], v[20:21]
	v_fmamk_f32 v23, v61, 0x3a800000, v148
	v_cvt_pk_bf16_f32 v22, v24, v25
	v_rsq_f32_e32 v24, v23
	v_cvt_pk_bf16_f32 v20, v28, v29
	v_cvt_pk_bf16_f32 v21, v30, v31
	v_cvt_pk_bf16_f32 v23, v26, v27
	global_store_dwordx4 v[32:33], v[20:23], off sc1
	s_mov_b64 s[2:3], -1
	s_nop 0
	v_add_u32_e32 v22, 0xb0, v0
	v_mul_f32_e32 v0, 0xbfb8aa3b, v24
	v_pk_mul_f32 v[20:21], v[16:17], v[0:1] op_sel_hi:[1,0]
	v_mad_i64_i32 v[2:3], s[20:21], v22, s65, v[2:3]
	v_exp_f32_e32 v20, v20
	v_exp_f32_e32 v21, v21
	v_mul_f32_e32 v22, v24, v24
	v_pk_mul_f32 v[24:25], v[18:19], v[0:1] op_sel_hi:[1,0]
	v_pk_add_f32 v[20:21], v[20:21], 1.0 op_sel_hi:[1,0]
	v_exp_f32_e32 v24, v24
	v_exp_f32_e32 v25, v25
	v_rcp_f32_e32 v20, v20
	v_rcp_f32_e32 v21, v21
	v_pk_add_f32 v[18:19], v[24:25], 1.0 op_sel_hi:[1,0]
	s_nop 0
	v_rcp_f32_e32 v18, v18
	v_rcp_f32_e32 v19, v19
	v_pk_mul_f32 v[16:17], v[22:23], v[20:21] op_sel_hi:[0,1]
	v_pk_mul_f32 v[20:21], v[4:5], v[0:1] op_sel_hi:[1,0]
	v_pk_mul_f32 v[12:13], v[12:13], v[16:17]
	v_exp_f32_e32 v20, v20
	v_exp_f32_e32 v21, v21
	v_pk_mul_f32 v[16:17], v[22:23], v[18:19] op_sel_hi:[0,1]
	v_pk_mul_f32 v[18:19], v[6:7], v[0:1] op_sel_hi:[1,0]
	v_pk_mul_f32 v[14:15], v[14:15], v[16:17]
	v_exp_f32_e32 v18, v18
	v_exp_f32_e32 v19, v19
	v_pk_add_f32 v[16:17], v[20:21], 1.0 op_sel_hi:[1,0]
	v_pk_mul_f32 v[6:7], v[6:7], v[10:11]
	v_rcp_f32_e32 v16, v16
	v_rcp_f32_e32 v17, v17
	v_pk_add_f32 v[10:11], v[18:19], 1.0 op_sel_hi:[1,0]
	v_pk_mul_f32 v[4:5], v[4:5], v[8:9]
	v_rcp_f32_e32 v10, v10
	v_rcp_f32_e32 v11, v11
	v_pk_mul_f32 v[8:9], v[22:23], v[16:17] op_sel_hi:[0,1]
	v_pk_mul_f32 v[4:5], v[4:5], v[8:9]
	v_pk_mul_f32 v[8:9], v[22:23], v[10:11] op_sel_hi:[0,1]
	v_pk_mul_f32 v[6:7], v[6:7], v[8:9]
	v_lshl_add_u64 v[8:9], v[2:3], 0, v[116:117]
	v_cvt_pk_bf16_f32 v2, v12, v13
	v_cvt_pk_bf16_f32 v3, v14, v15
	v_cvt_pk_bf16_f32 v4, v4, v5
	v_cvt_pk_bf16_f32 v5, v6, v7
	global_store_dwordx4 v[8:9], v[2:5], off sc1
	s_cbranch_vccnz .LBB0_103
	s_andn2_b64 vcc, exec, s[8:9]
	s_cbranch_vccnz .LBB0_102
	s_barrier
	s_branch .LBB0_102

; __device__ __forceinline__ int lane_id_() { int l; asm volatile("v_mbcnt_lo_u32_b32 %0, -1, 0\n\tv_mbcnt_hi_u32_b32 %0, -1, %0" : "=v"(l)); return l; }
; __device__ __forceinline__ unsigned xb_add(unsigned* p, unsigned v) { return __hip_atomic_fetch_add(p, v, __ATOMIC_RELAXED, __HIP_MEMORY_SCOPE_AGENT); }
; __device__ __forceinline__ void xcd_barrier(const XcdBarrier& b, int wave_s) {
;     asm volatile("s_waitcnt vmcnt(0)" ::: "memory");
;     __syncthreads();
;     if (wave_s == 0 && lane_id_() == 0) {
;         unsigned* bar = b.bar;
;         __builtin_amdgcn_s_waitcnt(0);
;         unsigned nloc = b.st[0], nx = b.st[1];
;         if (nloc == 0u) { xcd_barrier_complete(bar, b.x, nloc, nx); b.st[0] = nloc; b.st[1] = nx; }
;         const unsigned old = xb_add(&bar[XB_XSUB(b.x)], 1u);
;         const unsigned gen = old / nloc;
;         if (old + 1u == (gen + 1u) * nloc) {
;             __builtin_amdgcn_fence(__ATOMIC_RELEASE, "agent");
;             asm volatile("s_waitcnt vmcnt(0)" ::: "memory");
;             const unsigned og = xb_add(&bar[XB_TOP], 1u);
.LBB0_354:
	s_waitcnt vmcnt(0)
	s_and_b64 vcc, exec, s[2:3]
	s_waitcnt lgkmcnt(0)
	s_barrier
	s_cbranch_vccnz .LBB0_408
	v_mbcnt_lo_u32_b32 v0, -1, 0
	v_mbcnt_hi_u32_b32 v0, -1, v0
	s_nop 0
	v_cmp_eq_u32_e32 vcc, 0, v0
	s_and_saveexec_b64 s[6:7], vcc
	s_cbranch_execz .LBB0_407
	s_cmp_eq_u32 s101, 1
	s_cbranch_scc0 .Lglob_S3
	s_and_b32 s98, s33, 7
	s_lshl_b32 s99, s98, 2
	s_addk_i32 s99, 0x4800
	v_mov_b32_e32 v3, s99
	s_lshl_b32 s98, s98, 8
	s_addk_i32 s98, 0x4000
	v_mov_b32_e32 v0, s98
	v_mov_b32_e32 v1, 1
	global_atomic_add v2, v0, v1, s[44:45] sc0
	buffer_inv sc1
	s_waitcnt vmcnt(1)
	v_readfirstlane_b32 s98, v2
	s_nop 3
	s_add_u32 s99, s98, 1
	s_and_b32 s99, s99, 31
	s_lshr_b32 s98, s98, 5
	s_cmp_eq_u32 s99, 0
	s_cbranch_scc0 .Llw_S3
	global_atomic_add v3, v1, s[44:45]

; __device__ __forceinline__ unsigned xb_ld(unsigned* p)              { return __hip_atomic_load(p, __ATOMIC_RELAXED, __HIP_MEMORY_SCOPE_AGENT); }
; __device__ __forceinline__ unsigned xb_add(unsigned* p, unsigned v) { return __hip_atomic_fetch_add(p, v, __ATOMIC_RELAXED, __HIP_MEMORY_SCOPE_AGENT); }
; #define XB_SPIN(cond, bar) do { unsigned _sp = 0; while (cond) { __builtin_amdgcn_s_sleep(1); \
;     if ((++_sp & 255u) == 0u) { if (xb_ld(&(bar)[XB_TMO])) break; if (_sp > XB_SPIN_CAP) { atomicAdd(&(bar)[XB_TMO], 1u); break; } } } } while (0)
; __device__ __forceinline__ void xcd_barrier(const XcdBarrier& b, int wave_s) {
;     ...
;             __builtin_amdgcn_fence(__ATOMIC_ACQUIRE, "agent");
;             xb_add(&bar[XB_XGEN(b.x)], 1u);
;             asm volatile("s_waitcnt vmcnt(0)" ::: "memory");
;         } else {
;             XB_SPIN(xb_ld(&bar[XB_XGEN(b.x)]) == gen, bar);
;             __builtin_amdgcn_fence(__ATOMIC_ACQUIRE, "agent");
;             asm volatile("s_waitcnt vmcnt(0)" ::: "memory");
;         }
.Lla_S3:
	s_waitcnt vmcnt(0)
	s_branch .LBB0_407

; #define PG8_LAS __attribute__((address_space(3)))
; __device__ __forceinline__ unsigned pk_bf16(float lo, float hi) { typedef __bf16 b2_t __attribute__((ext_vector_type(2))); f32x2 v = {lo, hi}; b2_t b = __builtin_convertvector(v, b2_t); return __builtin_bit_cast(unsigned, b); }
; __device__ __forceinline__ float fast_sigmoid(float v) { return __builtin_amdgcn_rcpf(1.0f + __builtin_amdgcn_exp2f(-1.44269504089f * v)); }
;     __device__ __forceinline__ void operator()(const f32x4 (&acc)[2][2][4][2], const Unit& u, int wr, int wc, int fr, int fq, PG8_LAS unsigned char* lds, int wid) const {
;         const int t = u.pn >> 2; bf16_t* basep = O + (size_t)t * split_stride;
;         const int row0 = u.pm * BM + wr * 64 + fr, col0 = (u.pn & 3) * BM + wc * 32 + 8 * fq;
;         const bool act = t >= GELU_FROM;
; #pragma unroll
;         for (int ai = 0; ai < 2; ++ai)
; #pragma unroll
;             for (int m = 0; m < 4; ++m) {
;                 const float rstd = __builtin_amdgcn_rsqf(*(const PG8_LAS float*)(lds + PRE_SLOT + wid * 512 + (m & 1) * 256 + (fr + 16 * ((ai * 4 + m) >> 1)) * 4) * (1.0f / 1024.0f) + 1e-6f);
; #pragma unroll
;                 for (int bj = 0; bj < 2; ++bj) {
;                     float h[8];
; #pragma unroll
;                     for (int n = 0; n < 2; ++n)
; #pragma unroll
;                         for (int j = 0; j < 4; ++j) { float v = acc[ai][bj][m][n][j] * rstd;
;                             if (act) { const float z = 1.5957691216f * (v + 0.044715f * v * v * v); v = v * fast_sigmoid(z); }
;                             h[4 * n + j] = v; }
;                     u32x4 w; w.x = pk_bf16(h[0], h[1]); w.y = pk_bf16(h[2], h[3]); w.z = pk_bf16(h[4], h[5]); w.w = pk_bf16(h[6], h[7]);
;                     *(u32x4*)(basep + (size_t)(row0 + ai * HALF + m * 16) * 1024 + col0 + bj * HALF) = w;
.LBB0_432:
	s_ashr_i32 s39, s38, 31
	s_lshl_b64 s[38:39], s[38:39], 25
	s_add_u32 s38, s50, s38
	s_addc_u32 s39, s51, s39
	s_lshl_b32 s34, s34, 8
	s_and_b32 s34, s34, 0x300
	v_lshl_add_u32 v2, s36, 8, v144
	v_or_b32_e32 v0, s34, v147
	v_lshlrev_b32_e32 v0, 1, v0
	v_ashrrev_i32_e32 v3, 31, v2
	v_lshl_add_u64 v[124:125], s[38:39], 0, v[0:1]
	v_lshlrev_b64 v[126:127], 11, v[2:3]
	v_lshl_add_u64 v[126:127], v[124:125], 0, v[126:127]
	v_cvt_pk_bf16_f32 v128, v128, v129
	v_cvt_pk_bf16_f32 v129, v130, v131
	v_cvt_pk_bf16_f32 v130, v156, v157
	v_cvt_pk_bf16_f32 v131, v158, v159
	s_and_b64 vcc, exec, s[8:9]
	v_mul_f32_e32 v0, v120, v155
	global_store_dwordx4 v[126:127], v[128:131], off sc1
	s_cbranch_vccz .LBB0_576
	s_and_b64 vcc, exec, s[8:9]
	v_mul_f32_e32 v120, v121, v155
	s_cbranch_vccz .LBB0_577

; #define PG8_LAS __attribute__((address_space(3)))
; __device__ __forceinline__ unsigned pk_bf16(float lo, float hi) { typedef __bf16 b2_t __attribute__((ext_vector_type(2))); f32x2 v = {lo, hi}; b2_t b = __builtin_convertvector(v, b2_t); return __builtin_bit_cast(unsigned, b); }
; __device__ __forceinline__ float fast_sigmoid(float v) { return __builtin_amdgcn_rcpf(1.0f + __builtin_amdgcn_exp2f(-1.44269504089f * v)); }
;     __device__ __forceinline__ void operator()(const f32x4 (&acc)[2][2][4][2], const Unit& u, int wr, int wc, int fr, int fq, PG8_LAS unsigned char* lds, int wid) const {
;     ...
;                 const float rstd = __builtin_amdgcn_rsqf(*(const PG8_LAS float*)(lds + PRE_SLOT + wid * 512 + (m & 1) * 256 + (fr + 16 * ((ai * 4 + m) >> 1)) * 4) * (1.0f / 1024.0f) + 1e-6f);
; #pragma unroll
;                 for (int bj = 0; bj < 2; ++bj) {
;                     float h[8];
; #pragma unroll
;                     for (int n = 0; n < 2; ++n)
; #pragma unroll
;                         for (int j = 0; j < 4; ++j) { float v = acc[ai][bj][m][n][j] * rstd;
;                             if (act) { const float z = 1.5957691216f * (v + 0.044715f * v * v * v); v = v * fast_sigmoid(z); }
;                             h[4 * n + j] = v; }
;                     u32x4 w; w.x = pk_bf16(h[0], h[1]); w.y = pk_bf16(h[2], h[3]); w.z = pk_bf16(h[4], h[5]); w.w = pk_bf16(h[6], h[7]);
;                     *(u32x4*)(basep + (size_t)(row0 + ai * HALF + m * 16) * 1024 + col0 + bj * HALF) = w;
.LBB0_441:
	ds_read_b32 v123, v154 offset:256
	v_cvt_pk_bf16_f32 v120, v0, v120
	v_cvt_pk_bf16_f32 v121, v121, v122
	v_cvt_pk_bf16_f32 v122, v116, v117
	s_and_b64 vcc, exec, s[8:9]
	s_waitcnt lgkmcnt(0)
	v_fmamk_f32 v0, v123, 0x3a800000, v148
	v_rsq_f32_e32 v0, v0
	v_cvt_pk_bf16_f32 v123, v118, v119
	global_store_dwordx4 v[126:127], v[120:123], off offset:256 sc1
	v_mul_f32_e32 v112, v112, v0
	s_cbranch_vccz .LBB0_583
	s_and_b64 vcc, exec, s[8:9]
	v_mul_f32_e32 v113, v113, v0
	s_cbranch_vccz .LBB0_584

; #define PG8_LAS __attribute__((address_space(3)))
; __device__ __forceinline__ unsigned pk_bf16(float lo, float hi) { typedef __bf16 b2_t __attribute__((ext_vector_type(2))); f32x2 v = {lo, hi}; b2_t b = __builtin_convertvector(v, b2_t); return __builtin_bit_cast(unsigned, b); }
; __device__ __forceinline__ float fast_sigmoid(float v) { return __builtin_amdgcn_rcpf(1.0f + __builtin_amdgcn_exp2f(-1.44269504089f * v)); }
;     __device__ __forceinline__ void operator()(const f32x4 (&acc)[2][2][4][2], const Unit& u, int wr, int wc, int fr, int fq, PG8_LAS unsigned char* lds, int wid) const {
;     ...
;                 const float rstd = __builtin_amdgcn_rsqf(*(const PG8_LAS float*)(lds + PRE_SLOT + wid * 512 + (m & 1) * 256 + (fr + 16 * ((ai * 4 + m) >> 1)) * 4) * (1.0f / 1024.0f) + 1e-6f);
; #pragma unroll
;                 for (int bj = 0; bj < 2; ++bj) {
;                     float h[8];
; #pragma unroll
;                     for (int n = 0; n < 2; ++n)
; #pragma unroll
;                         for (int j = 0; j < 4; ++j) { float v = acc[ai][bj][m][n][j] * rstd;
;                             if (act) { const float z = 1.5957691216f * (v + 0.044715f * v * v * v); v = v * fast_sigmoid(z); }
;                             h[4 * n + j] = v; }
;                     u32x4 w; w.x = pk_bf16(h[0], h[1]); w.y = pk_bf16(h[2], h[3]); w.z = pk_bf16(h[4], h[5]); w.w = pk_bf16(h[6], h[7]);
;                     *(u32x4*)(basep + (size_t)(row0 + ai * HALF + m * 16) * 1024 + col0 + bj * HALF) = w;
.LBB0_450:
	v_or_b32_e32 v108, 16, v2
	v_ashrrev_i32_e32 v109, 31, v108
	v_lshlrev_b64 v[108:109], 11, v[108:109]
	v_lshl_add_u64 v[108:109], v[124:125], 0, v[108:109]
	v_cvt_pk_bf16_f32 v112, v112, v113
	v_cvt_pk_bf16_f32 v113, v114, v115
	v_cvt_pk_bf16_f32 v114, v116, v117
	v_cvt_pk_bf16_f32 v115, v110, v111
	s_and_b64 vcc, exec, s[8:9]
	v_mul_f32_e32 v104, v104, v0
	global_store_dwordx4 v[108:109], v[112:115], off sc1
	s_cbranch_vccz .LBB0_590
	s_and_b64 vcc, exec, s[8:9]
	v_mul_f32_e32 v105, v105, v0
	s_cbranch_vccz .LBB0_591

; #define PG8_LAS __attribute__((address_space(3)))
; __device__ __forceinline__ unsigned pk_bf16(float lo, float hi) { typedef __bf16 b2_t __attribute__((ext_vector_type(2))); f32x2 v = {lo, hi}; b2_t b = __builtin_convertvector(v, b2_t); return __builtin_bit_cast(unsigned, b); }
; __device__ __forceinline__ float fast_sigmoid(float v) { return __builtin_amdgcn_rcpf(1.0f + __builtin_amdgcn_exp2f(-1.44269504089f * v)); }
;     __device__ __forceinline__ void operator()(const f32x4 (&acc)[2][2][4][2], const Unit& u, int wr, int wc, int fr, int fq, PG8_LAS unsigned char* lds, int wid) const {
;     ...
;                 const float rstd = __builtin_amdgcn_rsqf(*(const PG8_LAS float*)(lds + PRE_SLOT + wid * 512 + (m & 1) * 256 + (fr + 16 * ((ai * 4 + m) >> 1)) * 4) * (1.0f / 1024.0f) + 1e-6f);
; #pragma unroll
;                 for (int bj = 0; bj < 2; ++bj) {
;                     float h[8];
; #pragma unroll
;                     for (int n = 0; n < 2; ++n)
; #pragma unroll
;                         for (int j = 0; j < 4; ++j) { float v = acc[ai][bj][m][n][j] * rstd;
;                             if (act) { const float z = 1.5957691216f * (v + 0.044715f * v * v * v); v = v * fast_sigmoid(z); }
;                             h[4 * n + j] = v; }
;                     u32x4 w; w.x = pk_bf16(h[0], h[1]); w.y = pk_bf16(h[2], h[3]); w.z = pk_bf16(h[4], h[5]); w.w = pk_bf16(h[6], h[7]);
;                     *(u32x4*)(basep + (size_t)(row0 + ai * HALF + m * 16) * 1024 + col0 + bj * HALF) = w;
.LBB0_459:
	ds_read_b32 v0, v154 offset:64
	v_cvt_pk_bf16_f32 v104, v104, v105
	v_cvt_pk_bf16_f32 v105, v106, v107
	v_cvt_pk_bf16_f32 v106, v100, v101
	v_cvt_pk_bf16_f32 v107, v102, v103
	s_waitcnt lgkmcnt(0)
	v_fmamk_f32 v0, v0, 0x3a800000, v148
	v_rsq_f32_e32 v0, v0
	s_and_b64 vcc, exec, s[8:9]
	global_store_dwordx4 v[108:109], v[104:107], off offset:256 sc1
	v_mul_f32_e32 v96, v96, v0
	s_cbranch_vccz .LBB0_597
	s_and_b64 vcc, exec, s[8:9]
	v_mul_f32_e32 v97, v97, v0
	s_cbranch_vccz .LBB0_598

; #define PG8_LAS __attribute__((address_space(3)))
; __device__ __forceinline__ unsigned pk_bf16(float lo, float hi) { typedef __bf16 b2_t __attribute__((ext_vector_type(2))); f32x2 v = {lo, hi}; b2_t b = __builtin_convertvector(v, b2_t); return __builtin_bit_cast(unsigned, b); }
; __device__ __forceinline__ float fast_sigmoid(float v) { return __builtin_amdgcn_rcpf(1.0f + __builtin_amdgcn_exp2f(-1.44269504089f * v)); }
;     __device__ __forceinline__ void operator()(const f32x4 (&acc)[2][2][4][2], const Unit& u, int wr, int wc, int fr, int fq, PG8_LAS unsigned char* lds, int wid) const {
;     ...
;                 const float rstd = __builtin_amdgcn_rsqf(*(const PG8_LAS float*)(lds + PRE_SLOT + wid * 512 + (m & 1) * 256 + (fr + 16 * ((ai * 4 + m) >> 1)) * 4) * (1.0f / 1024.0f) + 1e-6f);
; #pragma unroll
;                 for (int bj = 0; bj < 2; ++bj) {
;                     float h[8];
; #pragma unroll
;                     for (int n = 0; n < 2; ++n)
; #pragma unroll
;                         for (int j = 0; j < 4; ++j) { float v = acc[ai][bj][m][n][j] * rstd;
;                             if (act) { const float z = 1.5957691216f * (v + 0.044715f * v * v * v); v = v * fast_sigmoid(z); }
;                             h[4 * n + j] = v; }
;                     u32x4 w; w.x = pk_bf16(h[0], h[1]); w.y = pk_bf16(h[2], h[3]); w.z = pk_bf16(h[4], h[5]); w.w = pk_bf16(h[6], h[7]);
;                     *(u32x4*)(basep + (size_t)(row0 + ai * HALF + m * 16) * 1024 + col0 + bj * HALF) = w;
.LBB0_468:
	v_or_b32_e32 v92, 32, v2
	v_ashrrev_i32_e32 v93, 31, v92
	v_lshlrev_b64 v[92:93], 11, v[92:93]
	v_lshl_add_u64 v[92:93], v[124:125], 0, v[92:93]
	v_cvt_pk_bf16_f32 v96, v96, v97
	v_cvt_pk_bf16_f32 v97, v98, v99
	v_cvt_pk_bf16_f32 v98, v100, v101
	v_cvt_pk_bf16_f32 v99, v94, v95
	s_and_b64 vcc, exec, s[8:9]
	v_mul_f32_e32 v88, v88, v0
	global_store_dwordx4 v[92:93], v[96:99], off sc1
	s_cbranch_vccz .LBB0_604
	s_and_b64 vcc, exec, s[8:9]
	v_mul_f32_e32 v89, v89, v0
	s_cbranch_vccz .LBB0_605

; #define PG8_LAS __attribute__((address_space(3)))
; __device__ __forceinline__ unsigned pk_bf16(float lo, float hi) { typedef __bf16 b2_t __attribute__((ext_vector_type(2))); f32x2 v = {lo, hi}; b2_t b = __builtin_convertvector(v, b2_t); return __builtin_bit_cast(unsigned, b); }
; __device__ __forceinline__ float fast_sigmoid(float v) { return __builtin_amdgcn_rcpf(1.0f + __builtin_amdgcn_exp2f(-1.44269504089f * v)); }
;     __device__ __forceinline__ void operator()(const f32x4 (&acc)[2][2][4][2], const Unit& u, int wr, int wc, int fr, int fq, PG8_LAS unsigned char* lds, int wid) const {
;     ...
;                 const float rstd = __builtin_amdgcn_rsqf(*(const PG8_LAS float*)(lds + PRE_SLOT + wid * 512 + (m & 1) * 256 + (fr + 16 * ((ai * 4 + m) >> 1)) * 4) * (1.0f / 1024.0f) + 1e-6f);
; #pragma unroll
;                 for (int bj = 0; bj < 2; ++bj) {
;                     float h[8];
; #pragma unroll
;                     for (int n = 0; n < 2; ++n)
; #pragma unroll
;                         for (int j = 0; j < 4; ++j) { float v = acc[ai][bj][m][n][j] * rstd;
;                             if (act) { const float z = 1.5957691216f * (v + 0.044715f * v * v * v); v = v * fast_sigmoid(z); }
;                             h[4 * n + j] = v; }
;                     u32x4 w; w.x = pk_bf16(h[0], h[1]); w.y = pk_bf16(h[2], h[3]); w.z = pk_bf16(h[4], h[5]); w.w = pk_bf16(h[6], h[7]);
;                     *(u32x4*)(basep + (size_t)(row0 + ai * HALF + m * 16) * 1024 + col0 + bj * HALF) = w;
.LBB0_477:
	ds_read_b32 v0, v154 offset:320
	v_cvt_pk_bf16_f32 v88, v88, v89
	v_cvt_pk_bf16_f32 v89, v90, v91
	v_cvt_pk_bf16_f32 v90, v84, v85
	v_cvt_pk_bf16_f32 v91, v86, v87
	s_waitcnt lgkmcnt(0)
	v_fmamk_f32 v0, v0, 0x3a800000, v148
	v_rsq_f32_e32 v0, v0
	s_and_b64 vcc, exec, s[8:9]
	global_store_dwordx4 v[92:93], v[88:91], off offset:256 sc1
	v_mul_f32_e32 v80, v80, v0
	s_cbranch_vccz .LBB0_611
	s_and_b64 vcc, exec, s[8:9]
	v_mul_f32_e32 v81, v81, v0
	s_cbranch_vccz .LBB0_612

; #define PG8_LAS __attribute__((address_space(3)))
; __device__ __forceinline__ unsigned pk_bf16(float lo, float hi) { typedef __bf16 b2_t __attribute__((ext_vector_type(2))); f32x2 v = {lo, hi}; b2_t b = __builtin_convertvector(v, b2_t); return __builtin_bit_cast(unsigned, b); }
; __device__ __forceinline__ float fast_sigmoid(float v) { return __builtin_amdgcn_rcpf(1.0f + __builtin_amdgcn_exp2f(-1.44269504089f * v)); }
;     __device__ __forceinline__ void operator()(const f32x4 (&acc)[2][2][4][2], const Unit& u, int wr, int wc, int fr, int fq, PG8_LAS unsigned char* lds, int wid) const {
;     ...
;                 const float rstd = __builtin_amdgcn_rsqf(*(const PG8_LAS float*)(lds + PRE_SLOT + wid * 512 + (m & 1) * 256 + (fr + 16 * ((ai * 4 + m) >> 1)) * 4) * (1.0f / 1024.0f) + 1e-6f);
; #pragma unroll
;                 for (int bj = 0; bj < 2; ++bj) {
;                     float h[8];
; #pragma unroll
;                     for (int n = 0; n < 2; ++n)
; #pragma unroll
;                         for (int j = 0; j < 4; ++j) { float v = acc[ai][bj][m][n][j] * rstd;
;                             if (act) { const float z = 1.5957691216f * (v + 0.044715f * v * v * v); v = v * fast_sigmoid(z); }
;                             h[4 * n + j] = v; }
;                     u32x4 w; w.x = pk_bf16(h[0], h[1]); w.y = pk_bf16(h[2], h[3]); w.z = pk_bf16(h[4], h[5]); w.w = pk_bf16(h[6], h[7]);
;                     *(u32x4*)(basep + (size_t)(row0 + ai * HALF + m * 16) * 1024 + col0 + bj * HALF) = w;
.LBB0_486:
	v_or_b32_e32 v76, 48, v2
	v_ashrrev_i32_e32 v77, 31, v76
	v_lshlrev_b64 v[76:77], 11, v[76:77]
	v_lshl_add_u64 v[76:77], v[124:125], 0, v[76:77]
	v_cvt_pk_bf16_f32 v80, v80, v81
	v_cvt_pk_bf16_f32 v81, v82, v83
	v_cvt_pk_bf16_f32 v82, v84, v85
	v_cvt_pk_bf16_f32 v83, v78, v79
	s_and_b64 vcc, exec, s[8:9]
	v_mul_f32_e32 v72, v72, v0
	global_store_dwordx4 v[76:77], v[80:83], off sc1
	s_cbranch_vccz .LBB0_618
	s_and_b64 vcc, exec, s[8:9]
	v_mul_f32_e32 v73, v73, v0
	s_cbranch_vccz .LBB0_619

; #define PG8_LAS __attribute__((address_space(3)))
; __device__ __forceinline__ unsigned pk_bf16(float lo, float hi) { typedef __bf16 b2_t __attribute__((ext_vector_type(2))); f32x2 v = {lo, hi}; b2_t b = __builtin_convertvector(v, b2_t); return __builtin_bit_cast(unsigned, b); }
; __device__ __forceinline__ float fast_sigmoid(float v) { return __builtin_amdgcn_rcpf(1.0f + __builtin_amdgcn_exp2f(-1.44269504089f * v)); }
;     __device__ __forceinline__ void operator()(const f32x4 (&acc)[2][2][4][2], const Unit& u, int wr, int wc, int fr, int fq, PG8_LAS unsigned char* lds, int wid) const {
;     ...
;                 const float rstd = __builtin_amdgcn_rsqf(*(const PG8_LAS float*)(lds + PRE_SLOT + wid * 512 + (m & 1) * 256 + (fr + 16 * ((ai * 4 + m) >> 1)) * 4) * (1.0f / 1024.0f) + 1e-6f);
; #pragma unroll
;                 for (int bj = 0; bj < 2; ++bj) {
;                     float h[8];
; #pragma unroll
;                     for (int n = 0; n < 2; ++n)
; #pragma unroll
;                         for (int j = 0; j < 4; ++j) { float v = acc[ai][bj][m][n][j] * rstd;
;                             if (act) { const float z = 1.5957691216f * (v + 0.044715f * v * v * v); v = v * fast_sigmoid(z); }
;                             h[4 * n + j] = v; }
;                     u32x4 w; w.x = pk_bf16(h[0], h[1]); w.y = pk_bf16(h[2], h[3]); w.z = pk_bf16(h[4], h[5]); w.w = pk_bf16(h[6], h[7]);
;                     *(u32x4*)(basep + (size_t)(row0 + ai * HALF + m * 16) * 1024 + col0 + bj * HALF) = w;
.LBB0_495:
	ds_read_b32 v0, v154 offset:128
	v_cvt_pk_bf16_f32 v72, v72, v73
	v_cvt_pk_bf16_f32 v73, v74, v75
	v_cvt_pk_bf16_f32 v74, v68, v69
	v_cvt_pk_bf16_f32 v75, v70, v71
	s_waitcnt lgkmcnt(0)
	v_fmamk_f32 v0, v0, 0x3a800000, v148
	v_rsq_f32_e32 v0, v0
	s_and_b64 vcc, exec, s[8:9]
	global_store_dwordx4 v[76:77], v[72:75], off offset:256 sc1
	v_mul_f32_e32 v64, v64, v0
	s_cbranch_vccz .LBB0_625
	s_and_b64 vcc, exec, s[8:9]
	v_mul_f32_e32 v65, v65, v0
	s_cbranch_vccz .LBB0_626

; #define PG8_LAS __attribute__((address_space(3)))
; __device__ __forceinline__ unsigned pk_bf16(float lo, float hi) { typedef __bf16 b2_t __attribute__((ext_vector_type(2))); f32x2 v = {lo, hi}; b2_t b = __builtin_convertvector(v, b2_t); return __builtin_bit_cast(unsigned, b); }
; __device__ __forceinline__ float fast_sigmoid(float v) { return __builtin_amdgcn_rcpf(1.0f + __builtin_amdgcn_exp2f(-1.44269504089f * v)); }
;     __device__ __forceinline__ void operator()(const f32x4 (&acc)[2][2][4][2], const Unit& u, int wr, int wc, int fr, int fq, PG8_LAS unsigned char* lds, int wid) const {
;     ...
;                 const float rstd = __builtin_amdgcn_rsqf(*(const PG8_LAS float*)(lds + PRE_SLOT + wid * 512 + (m & 1) * 256 + (fr + 16 * ((ai * 4 + m) >> 1)) * 4) * (1.0f / 1024.0f) + 1e-6f);
; #pragma unroll
;                 for (int bj = 0; bj < 2; ++bj) {
;                     float h[8];
; #pragma unroll
;                     for (int n = 0; n < 2; ++n)
; #pragma unroll
;                         for (int j = 0; j < 4; ++j) { float v = acc[ai][bj][m][n][j] * rstd;
;                             if (act) { const float z = 1.5957691216f * (v + 0.044715f * v * v * v); v = v * fast_sigmoid(z); }
;                             h[4 * n + j] = v; }
;                     u32x4 w; w.x = pk_bf16(h[0], h[1]); w.y = pk_bf16(h[2], h[3]); w.z = pk_bf16(h[4], h[5]); w.w = pk_bf16(h[6], h[7]);
;                     *(u32x4*)(basep + (size_t)(row0 + ai * HALF + m * 16) * 1024 + col0 + bj * HALF) = w;
.LBB0_504:
	v_lshlrev_b64 v[60:61], 11, v[2:3]
	v_lshl_add_u64 v[60:61], v[124:125], 0, v[60:61]
	v_cvt_pk_bf16_f32 v64, v64, v65
	v_cvt_pk_bf16_f32 v65, v66, v67
	v_cvt_pk_bf16_f32 v67, v62, v63
	v_add_co_u32_e32 v62, vcc, 0x40000, v60
	v_cvt_pk_bf16_f32 v66, v68, v69
	s_nop 0
	v_addc_co_u32_e32 v63, vcc, 0, v61, vcc
	s_and_b64 vcc, exec, s[8:9]
	v_mul_f32_e32 v56, v56, v0
	global_store_dwordx4 v[62:63], v[64:67], off sc1
	s_cbranch_vccz .LBB0_632
	s_and_b64 vcc, exec, s[8:9]
	v_mul_f32_e32 v57, v57, v0
	s_cbranch_vccz .LBB0_633

; #define PG8_LAS __attribute__((address_space(3)))
; __device__ __forceinline__ unsigned pk_bf16(float lo, float hi) { typedef __bf16 b2_t __attribute__((ext_vector_type(2))); f32x2 v = {lo, hi}; b2_t b = __builtin_convertvector(v, b2_t); return __builtin_bit_cast(unsigned, b); }
; __device__ __forceinline__ float fast_sigmoid(float v) { return __builtin_amdgcn_rcpf(1.0f + __builtin_amdgcn_exp2f(-1.44269504089f * v)); }
;     __device__ __forceinline__ void operator()(const f32x4 (&acc)[2][2][4][2], const Unit& u, int wr, int wc, int fr, int fq, PG8_LAS unsigned char* lds, int wid) const {
;     ...
;                 const float rstd = __builtin_amdgcn_rsqf(*(const PG8_LAS float*)(lds + PRE_SLOT + wid * 512 + (m & 1) * 256 + (fr + 16 * ((ai * 4 + m) >> 1)) * 4) * (1.0f / 1024.0f) + 1e-6f);
; #pragma unroll
;                 for (int bj = 0; bj < 2; ++bj) {
;                     float h[8];
; #pragma unroll
;                     for (int n = 0; n < 2; ++n)
; #pragma unroll
;                         for (int j = 0; j < 4; ++j) { float v = acc[ai][bj][m][n][j] * rstd;
;                             if (act) { const float z = 1.5957691216f * (v + 0.044715f * v * v * v); v = v * fast_sigmoid(z); }
;                             h[4 * n + j] = v; }
;                     u32x4 w; w.x = pk_bf16(h[0], h[1]); w.y = pk_bf16(h[2], h[3]); w.z = pk_bf16(h[4], h[5]); w.w = pk_bf16(h[6], h[7]);
;                     *(u32x4*)(basep + (size_t)(row0 + ai * HALF + m * 16) * 1024 + col0 + bj * HALF) = w;
.LBB0_513:
	ds_read_b32 v0, v154 offset:384
	v_lshl_add_u64 v[60:61], v[60:61], 0, s[12:13]
	v_cvt_pk_bf16_f32 v56, v56, v57
	v_cvt_pk_bf16_f32 v57, v58, v59
	v_cvt_pk_bf16_f32 v58, v52, v53
	s_waitcnt lgkmcnt(0)
	v_fmamk_f32 v0, v0, 0x3a800000, v148
	v_rsq_f32_e32 v0, v0
	v_cvt_pk_bf16_f32 v59, v54, v55
	s_and_b64 vcc, exec, s[8:9]
	global_store_dwordx4 v[60:61], v[56:59], off offset:256 sc1
	v_mul_f32_e32 v48, v48, v0
	s_cbranch_vccz .LBB0_639
	s_and_b64 vcc, exec, s[8:9]
	v_mul_f32_e32 v49, v49, v0
	s_cbranch_vccz .LBB0_640

; #define PG8_LAS __attribute__((address_space(3)))
; __device__ __forceinline__ unsigned pk_bf16(float lo, float hi) { typedef __bf16 b2_t __attribute__((ext_vector_type(2))); f32x2 v = {lo, hi}; b2_t b = __builtin_convertvector(v, b2_t); return __builtin_bit_cast(unsigned, b); }
; __device__ __forceinline__ float fast_sigmoid(float v) { return __builtin_amdgcn_rcpf(1.0f + __builtin_amdgcn_exp2f(-1.44269504089f * v)); }
;     __device__ __forceinline__ void operator()(const f32x4 (&acc)[2][2][4][2], const Unit& u, int wr, int wc, int fr, int fq, PG8_LAS unsigned char* lds, int wid) const {
;     ...
;                 const float rstd = __builtin_amdgcn_rsqf(*(const PG8_LAS float*)(lds + PRE_SLOT + wid * 512 + (m & 1) * 256 + (fr + 16 * ((ai * 4 + m) >> 1)) * 4) * (1.0f / 1024.0f) + 1e-6f);
; #pragma unroll
;                 for (int bj = 0; bj < 2; ++bj) {
;                     float h[8];
; #pragma unroll
;                     for (int n = 0; n < 2; ++n)
; #pragma unroll
;                         for (int j = 0; j < 4; ++j) { float v = acc[ai][bj][m][n][j] * rstd;
;                             if (act) { const float z = 1.5957691216f * (v + 0.044715f * v * v * v); v = v * fast_sigmoid(z); }
;                             h[4 * n + j] = v; }
;                     u32x4 w; w.x = pk_bf16(h[0], h[1]); w.y = pk_bf16(h[2], h[3]); w.z = pk_bf16(h[4], h[5]); w.w = pk_bf16(h[6], h[7]);
;                     *(u32x4*)(basep + (size_t)(row0 + ai * HALF + m * 16) * 1024 + col0 + bj * HALF) = w;
.LBB0_522:
	v_lshlrev_b64 v[44:45], 11, v[2:3]
	v_lshl_add_u64 v[44:45], v[124:125], 0, v[44:45]
	v_cvt_pk_bf16_f32 v48, v48, v49
	v_cvt_pk_bf16_f32 v49, v50, v51
	v_cvt_pk_bf16_f32 v51, v46, v47
	v_add_co_u32_e32 v46, vcc, 0x48000, v44
	v_cvt_pk_bf16_f32 v50, v52, v53
	s_nop 0
	v_addc_co_u32_e32 v47, vcc, 0, v45, vcc
	s_and_b64 vcc, exec, s[8:9]
	v_mul_f32_e32 v40, v40, v0
	global_store_dwordx4 v[46:47], v[48:51], off sc1
	s_cbranch_vccz .LBB0_646
	s_and_b64 vcc, exec, s[8:9]
	v_mul_f32_e32 v41, v41, v0
	s_cbranch_vccz .LBB0_647

; #define PG8_LAS __attribute__((address_space(3)))
; __device__ __forceinline__ unsigned pk_bf16(float lo, float hi) { typedef __bf16 b2_t __attribute__((ext_vector_type(2))); f32x2 v = {lo, hi}; b2_t b = __builtin_convertvector(v, b2_t); return __builtin_bit_cast(unsigned, b); }
; __device__ __forceinline__ float fast_sigmoid(float v) { return __builtin_amdgcn_rcpf(1.0f + __builtin_amdgcn_exp2f(-1.44269504089f * v)); }
;     __device__ __forceinline__ void operator()(const f32x4 (&acc)[2][2][4][2], const Unit& u, int wr, int wc, int fr, int fq, PG8_LAS unsigned char* lds, int wid) const {
;     ...
;                 const float rstd = __builtin_amdgcn_rsqf(*(const PG8_LAS float*)(lds + PRE_SLOT + wid * 512 + (m & 1) * 256 + (fr + 16 * ((ai * 4 + m) >> 1)) * 4) * (1.0f / 1024.0f) + 1e-6f);
; #pragma unroll
;                 for (int bj = 0; bj < 2; ++bj) {
;                     float h[8];
; #pragma unroll
;                     for (int n = 0; n < 2; ++n)
; #pragma unroll
;                         for (int j = 0; j < 4; ++j) { float v = acc[ai][bj][m][n][j] * rstd;
;                             if (act) { const float z = 1.5957691216f * (v + 0.044715f * v * v * v); v = v * fast_sigmoid(z); }
;                             h[4 * n + j] = v; }
;                     u32x4 w; w.x = pk_bf16(h[0], h[1]); w.y = pk_bf16(h[2], h[3]); w.z = pk_bf16(h[4], h[5]); w.w = pk_bf16(h[6], h[7]);
;                     *(u32x4*)(basep + (size_t)(row0 + ai * HALF + m * 16) * 1024 + col0 + bj * HALF) = w;
.LBB0_531:
	ds_read_b32 v0, v154 offset:192
	v_lshl_add_u64 v[44:45], v[44:45], 0, s[18:19]
	v_cvt_pk_bf16_f32 v40, v40, v41
	v_cvt_pk_bf16_f32 v41, v42, v43
	v_cvt_pk_bf16_f32 v42, v36, v37
	s_waitcnt lgkmcnt(0)
	v_fmamk_f32 v0, v0, 0x3a800000, v148
	v_rsq_f32_e32 v0, v0
	v_cvt_pk_bf16_f32 v43, v38, v39
	s_and_b64 vcc, exec, s[8:9]
	global_store_dwordx4 v[44:45], v[40:43], off offset:256 sc1
	v_mul_f32_e32 v32, v32, v0
	s_cbranch_vccz .LBB0_653
	s_and_b64 vcc, exec, s[8:9]
	v_mul_f32_e32 v33, v33, v0
	s_cbranch_vccz .LBB0_654

; #define PG8_LAS __attribute__((address_space(3)))
; __device__ __forceinline__ unsigned pk_bf16(float lo, float hi) { typedef __bf16 b2_t __attribute__((ext_vector_type(2))); f32x2 v = {lo, hi}; b2_t b = __builtin_convertvector(v, b2_t); return __builtin_bit_cast(unsigned, b); }
; __device__ __forceinline__ float fast_sigmoid(float v) { return __builtin_amdgcn_rcpf(1.0f + __builtin_amdgcn_exp2f(-1.44269504089f * v)); }
;     __device__ __forceinline__ void operator()(const f32x4 (&acc)[2][2][4][2], const Unit& u, int wr, int wc, int fr, int fq, PG8_LAS unsigned char* lds, int wid) const {
;     ...
;                 const float rstd = __builtin_amdgcn_rsqf(*(const PG8_LAS float*)(lds + PRE_SLOT + wid * 512 + (m & 1) * 256 + (fr + 16 * ((ai * 4 + m) >> 1)) * 4) * (1.0f / 1024.0f) + 1e-6f);
; #pragma unroll
;                 for (int bj = 0; bj < 2; ++bj) {
;                     float h[8];
; #pragma unroll
;                     for (int n = 0; n < 2; ++n)
; #pragma unroll
;                         for (int j = 0; j < 4; ++j) { float v = acc[ai][bj][m][n][j] * rstd;
;                             if (act) { const float z = 1.5957691216f * (v + 0.044715f * v * v * v); v = v * fast_sigmoid(z); }
;                             h[4 * n + j] = v; }
;                     u32x4 w; w.x = pk_bf16(h[0], h[1]); w.y = pk_bf16(h[2], h[3]); w.z = pk_bf16(h[4], h[5]); w.w = pk_bf16(h[6], h[7]);
;                     *(u32x4*)(basep + (size_t)(row0 + ai * HALF + m * 16) * 1024 + col0 + bj * HALF) = w;
.LBB0_540:
	v_lshlrev_b64 v[28:29], 11, v[2:3]
	v_lshl_add_u64 v[28:29], v[124:125], 0, v[28:29]
	v_cvt_pk_bf16_f32 v32, v32, v33
	v_cvt_pk_bf16_f32 v33, v34, v35
	v_cvt_pk_bf16_f32 v35, v30, v31
	v_add_co_u32_e32 v30, vcc, 0x50000, v28
	v_cvt_pk_bf16_f32 v34, v36, v37
	s_nop 0
	v_addc_co_u32_e32 v31, vcc, 0, v29, vcc
	s_and_b64 vcc, exec, s[8:9]
	v_mul_f32_e32 v24, v24, v0
	global_store_dwordx4 v[30:31], v[32:35], off sc1
	s_cbranch_vccz .LBB0_660
	s_and_b64 vcc, exec, s[8:9]
	v_mul_f32_e32 v25, v25, v0
	s_cbranch_vccz .LBB0_661

; #define PG8_LAS __attribute__((address_space(3)))
; __device__ __forceinline__ unsigned pk_bf16(float lo, float hi) { typedef __bf16 b2_t __attribute__((ext_vector_type(2))); f32x2 v = {lo, hi}; b2_t b = __builtin_convertvector(v, b2_t); return __builtin_bit_cast(unsigned, b); }
; __device__ __forceinline__ float fast_sigmoid(float v) { return __builtin_amdgcn_rcpf(1.0f + __builtin_amdgcn_exp2f(-1.44269504089f * v)); }
;     __device__ __forceinline__ void operator()(const f32x4 (&acc)[2][2][4][2], const Unit& u, int wr, int wc, int fr, int fq, PG8_LAS unsigned char* lds, int wid) const {
;     ...
;                 const float rstd = __builtin_amdgcn_rsqf(*(const PG8_LAS float*)(lds + PRE_SLOT + wid * 512 + (m & 1) * 256 + (fr + 16 * ((ai * 4 + m) >> 1)) * 4) * (1.0f / 1024.0f) + 1e-6f);
; #pragma unroll
;                 for (int bj = 0; bj < 2; ++bj) {
;                     float h[8];
; #pragma unroll
;                     for (int n = 0; n < 2; ++n)
; #pragma unroll
;                         for (int j = 0; j < 4; ++j) { float v = acc[ai][bj][m][n][j] * rstd;
;                             if (act) { const float z = 1.5957691216f * (v + 0.044715f * v * v * v); v = v * fast_sigmoid(z); }
;                             h[4 * n + j] = v; }
;                     u32x4 w; w.x = pk_bf16(h[0], h[1]); w.y = pk_bf16(h[2], h[3]); w.z = pk_bf16(h[4], h[5]); w.w = pk_bf16(h[6], h[7]);
;                     *(u32x4*)(basep + (size_t)(row0 + ai * HALF + m * 16) * 1024 + col0 + bj * HALF) = w;
.LBB0_549:
	ds_read_b32 v0, v154 offset:448
	v_lshl_add_u64 v[28:29], v[28:29], 0, s[20:21]
	v_cvt_pk_bf16_f32 v24, v24, v25
	v_cvt_pk_bf16_f32 v25, v26, v27
	v_cvt_pk_bf16_f32 v26, v20, v21
	s_waitcnt lgkmcnt(0)
	v_fmamk_f32 v0, v0, 0x3a800000, v148
	v_rsq_f32_e32 v0, v0
	v_cvt_pk_bf16_f32 v27, v22, v23
	s_and_b64 vcc, exec, s[8:9]
	global_store_dwordx4 v[28:29], v[24:27], off offset:256 sc1
	v_mul_f32_e32 v16, v16, v0
	s_cbranch_vccz .LBB0_667
	s_and_b64 vcc, exec, s[8:9]
	v_mul_f32_e32 v17, v17, v0
	s_cbranch_vccz .LBB0_668

; #define PG8_LAS __attribute__((address_space(3)))
; __device__ __forceinline__ unsigned pk_bf16(float lo, float hi) { typedef __bf16 b2_t __attribute__((ext_vector_type(2))); f32x2 v = {lo, hi}; b2_t b = __builtin_convertvector(v, b2_t); return __builtin_bit_cast(unsigned, b); }
; __device__ __forceinline__ float fast_sigmoid(float v) { return __builtin_amdgcn_rcpf(1.0f + __builtin_amdgcn_exp2f(-1.44269504089f * v)); }
;     __device__ __forceinline__ void operator()(const f32x4 (&acc)[2][2][4][2], const Unit& u, int wr, int wc, int fr, int fq, PG8_LAS unsigned char* lds, int wid) const {
;     ...
;                 const float rstd = __builtin_amdgcn_rsqf(*(const PG8_LAS float*)(lds + PRE_SLOT + wid * 512 + (m & 1) * 256 + (fr + 16 * ((ai * 4 + m) >> 1)) * 4) * (1.0f / 1024.0f) + 1e-6f);
; #pragma unroll
;                 for (int bj = 0; bj < 2; ++bj) {
;                     float h[8];
; #pragma unroll
;                     for (int n = 0; n < 2; ++n)
; #pragma unroll
;                         for (int j = 0; j < 4; ++j) { float v = acc[ai][bj][m][n][j] * rstd;
;                             if (act) { const float z = 1.5957691216f * (v + 0.044715f * v * v * v); v = v * fast_sigmoid(z); }
;                             h[4 * n + j] = v; }
;                     u32x4 w; w.x = pk_bf16(h[0], h[1]); w.y = pk_bf16(h[2], h[3]); w.z = pk_bf16(h[4], h[5]); w.w = pk_bf16(h[6], h[7]);
;                     *(u32x4*)(basep + (size_t)(row0 + ai * HALF + m * 16) * 1024 + col0 + bj * HALF) = w;
.LBB0_558:
	v_lshlrev_b64 v[2:3], 11, v[2:3]
	v_lshl_add_u64 v[2:3], v[124:125], 0, v[2:3]
	v_cvt_pk_bf16_f32 v16, v16, v17
	v_cvt_pk_bf16_f32 v17, v18, v19
	v_cvt_pk_bf16_f32 v18, v12, v13
	v_add_co_u32_e32 v12, vcc, 0x58000, v2
	v_cvt_pk_bf16_f32 v19, v14, v15
	s_nop 0
	v_addc_co_u32_e32 v13, vcc, 0, v3, vcc
	s_and_b64 vcc, exec, s[8:9]
	v_mul_f32_e32 v8, v8, v0
	global_store_dwordx4 v[12:13], v[16:19], off sc1
	s_cbranch_vccz .LBB0_674
	s_and_b64 vcc, exec, s[8:9]
	v_mul_f32_e32 v9, v9, v0
	s_cbranch_vccz .LBB0_675

; __device__ __forceinline__ unsigned pk_bf16(float lo, float hi) { typedef __bf16 b2_t __attribute__((ext_vector_type(2))); f32x2 v = {lo, hi}; b2_t b = __builtin_convertvector(v, b2_t); return __builtin_bit_cast(unsigned, b); }
;     __device__ __forceinline__ void operator()(const f32x4 (&acc)[2][2][4][2], const Unit& u, int wr, int wc, int fr, int fq, PG8_LAS unsigned char* lds, int wid) const {
;     ...
;                     u32x4 w; w.x = pk_bf16(h[0], h[1]); w.y = pk_bf16(h[2], h[3]); w.z = pk_bf16(h[4], h[5]); w.w = pk_bf16(h[6], h[7]);
;                     *(u32x4*)(basep + (size_t)(row0 + ai * HALF + m * 16) * 1024 + col0 + bj * HALF) = w;
;                 }
;             }
;     }
.LBB0_567:
	v_lshl_add_u64 v[12:13], v[2:3], 0, s[22:23]
	v_cvt_pk_bf16_f32 v2, v8, v9
	v_cvt_pk_bf16_f32 v3, v10, v11
	v_cvt_pk_bf16_f32 v4, v4, v5
	v_cvt_pk_bf16_f32 v5, v6, v0
	s_andn2_b64 vcc, exec, s[6:7]
	s_mov_b64 s[6:7], -1
	global_store_dwordx4 v[12:13], v[2:5], off offset:256 sc1
	s_cbranch_vccnz .LBB0_415
	s_andn2_b64 vcc, exec, s[14:15]
	s_cbranch_vccnz .LBB0_414
	s_barrier
	s_branch .LBB0_414

; __device__ __forceinline__ int lane_id_() { int l; asm volatile("v_mbcnt_lo_u32_b32 %0, -1, 0\n\tv_mbcnt_hi_u32_b32 %0, -1, %0" : "=v"(l)); return l; }
; __device__ __forceinline__ unsigned xb_add(unsigned* p, unsigned v) { return __hip_atomic_fetch_add(p, v, __ATOMIC_RELAXED, __HIP_MEMORY_SCOPE_AGENT); }
; __device__ __forceinline__ void xcd_barrier(const XcdBarrier& b, int wave_s) {
;     asm volatile("s_waitcnt vmcnt(0)" ::: "memory");
;     __syncthreads();
;     if (wave_s == 0 && lane_id_() == 0) {
;         unsigned* bar = b.bar;
;         __builtin_amdgcn_s_waitcnt(0);
;         unsigned nloc = b.st[0], nx = b.st[1];
;         if (nloc == 0u) { xcd_barrier_complete(bar, b.x, nloc, nx); b.st[0] = nloc; b.st[1] = nx; }
;         const unsigned old = xb_add(&bar[XB_XSUB(b.x)], 1u);
;         const unsigned gen = old / nloc;
;         if (old + 1u == (gen + 1u) * nloc) {
;             __builtin_amdgcn_fence(__ATOMIC_RELEASE, "agent");
;             asm volatile("s_waitcnt vmcnt(0)" ::: "memory");
;             const unsigned og = xb_add(&bar[XB_TOP], 1u);
.LBB0_682:
	s_waitcnt vmcnt(0)
	s_and_b64 vcc, exec, s[2:3]
	s_waitcnt vmcnt(0)
	s_barrier
	s_cbranch_vccnz .LBB0_736
	v_mbcnt_lo_u32_b32 v0, -1, 0
	v_mbcnt_hi_u32_b32 v0, -1, v0
	s_nop 0
	v_cmp_eq_u32_e32 vcc, 0, v0
	s_and_saveexec_b64 s[6:7], vcc
	s_cbranch_execz .LBB0_735
	s_cmp_eq_u32 s101, 1
	s_cbranch_scc0 .Lglob_S4
	s_and_b32 s98, s33, 7
	s_lshl_b32 s99, s98, 2
	s_addk_i32 s99, 0x4800
	v_mov_b32_e32 v3, s99
	s_lshl_b32 s98, s98, 8
	s_addk_i32 s98, 0x4000
	v_mov_b32_e32 v0, s98
	v_mov_b32_e32 v1, 1
	global_atomic_add v2, v0, v1, s[44:45] sc0
	buffer_inv sc1
	s_waitcnt vmcnt(1)
	v_readfirstlane_b32 s98, v2
	s_nop 3
	s_add_u32 s99, s98, 1
	s_and_b32 s99, s99, 31
	s_lshr_b32 s98, s98, 5
	s_cmp_eq_u32 s99, 0
	s_cbranch_scc0 .Llw_S4
	global_atomic_add v3, v1, s[44:45]
	s_branch .Lla_S4

; __device__ __forceinline__ void attn_phase2(LAS unsigned char* lds, const bf16* Q, const bf16* K, const bf16* V, bf16* O, const float* qg, const float* kg, int gw, int ngw, int wave_s) {
;     ...
;         ATT_STORE(oa0, oa1, qblk0);
;         ATT_STORE(ob0, ob1, qblk1);
.LBB0_740:
	v_cvt_pk_bf16_f32 v1, v64, s0
	ds_write_b16 v180, v1
	v_cvt_pk_bf16_f32 v1, v48, s0
	ds_write_b16 v180, v1 offset:64
	v_cvt_pk_bf16_f32 v1, v65, s0
	ds_write_b16 v180, v1 offset:144
	v_cvt_pk_bf16_f32 v1, v49, s0
	ds_write_b16 v180, v1 offset:208
	v_cvt_pk_bf16_f32 v1, v66, s0
	ds_write_b16 v180, v1 offset:288
	v_cvt_pk_bf16_f32 v1, v50, s0
	ds_write_b16 v180, v1 offset:352
	v_cvt_pk_bf16_f32 v1, v67, s0
	ds_write_b16 v180, v1 offset:432
	v_cvt_pk_bf16_f32 v1, v51, s0
	ds_write_b16 v180, v1 offset:496
	v_cvt_pk_bf16_f32 v1, v68, s0
	ds_write_b16 v180, v1 offset:1152
	v_cvt_pk_bf16_f32 v1, v52, s0
	ds_write_b16 v180, v1 offset:1216
	v_cvt_pk_bf16_f32 v1, v69, s0
	ds_write_b16 v180, v1 offset:1296
	v_cvt_pk_bf16_f32 v1, v53, s0
	ds_write_b16 v180, v1 offset:1360
	v_cvt_pk_bf16_f32 v1, v70, s0
	ds_write_b16 v180, v1 offset:1440
	v_cvt_pk_bf16_f32 v1, v54, s0
	ds_write_b16 v180, v1 offset:1504
	v_cvt_pk_bf16_f32 v1, v71, s0
	ds_write_b16 v180, v1 offset:1584
	v_cvt_pk_bf16_f32 v1, v55, s0
	ds_write_b16 v180, v1 offset:1648
	v_cvt_pk_bf16_f32 v1, v72, s0
	ds_write_b16 v180, v1 offset:2304
	v_cvt_pk_bf16_f32 v1, v56, s0
	ds_write_b16 v180, v1 offset:2368
	v_cvt_pk_bf16_f32 v1, v73, s0
	ds_write_b16 v180, v1 offset:2448
	v_cvt_pk_bf16_f32 v1, v57, s0
	ds_write_b16 v180, v1 offset:2512
	v_cvt_pk_bf16_f32 v1, v74, s0
	ds_write_b16 v180, v1 offset:2592
	v_cvt_pk_bf16_f32 v1, v58, s0
	ds_write_b16 v180, v1 offset:2656
	v_cvt_pk_bf16_f32 v1, v75, s0
	ds_write_b16 v180, v1 offset:2736
	v_cvt_pk_bf16_f32 v1, v59, s0
	ds_write_b16 v180, v1 offset:2800
	v_cvt_pk_bf16_f32 v1, v76, s0
	ds_write_b16 v180, v1 offset:3456
	v_cvt_pk_bf16_f32 v1, v60, s0
	ds_write_b16 v180, v1 offset:3520
	v_cvt_pk_bf16_f32 v1, v77, s0
	ds_write_b16 v180, v1 offset:3600
	v_cvt_pk_bf16_f32 v1, v61, s0
	ds_write_b16 v180, v1 offset:3664
	v_cvt_pk_bf16_f32 v1, v78, s0
	ds_write_b16 v180, v1 offset:3744
	v_cvt_pk_bf16_f32 v1, v62, s0
	ds_write_b16 v180, v1 offset:3808
	v_cvt_pk_bf16_f32 v1, v79, s0
	v_or_b32_e32 v2, s95, v176
	ds_write_b16 v180, v1 offset:3888
	v_cvt_pk_bf16_f32 v1, v63, s0
	v_ashrrev_i32_e32 v3, 31, v2
	ds_write_b16 v180, v1 offset:3952
	v_lshlrev_b64 v[2:3], 11, v[2:3]
	v_lshl_add_u64 v[6:7], s[50:51], 0, v[2:3]
	s_lshl_b32 s72, s94, 1
	ds_read_b128 v[2:5], v182
	v_lshl_add_u64 v[6:7], v[6:7], 0, s[72:73]
	v_mov_b32_e32 v169, v0
	v_lshl_add_u64 v[10:11], v[6:7], 0, v[168:169]
	ds_read_b128 v[6:9], v183
	s_waitcnt lgkmcnt(1)
	global_store_dwordx4 v[10:11], v[2:5], off sc1
	v_cvt_pk_bf16_f32 v1, v32, s0
	s_mov_b32 s42, 0x8000
	v_add_co_u32_e32 v2, vcc, s90, v10
	s_add_i32 s63, s63, s99
	s_nop 0
	v_addc_co_u32_e32 v3, vcc, 0, v11, vcc
	s_waitcnt lgkmcnt(0)
	global_store_dwordx4 v[2:3], v[6:9], off sc1
	ds_read_b128 v[2:5], v183 offset:1152
	ds_read_b128 v[6:9], v183 offset:2304
	ds_write_b16 v180, v1
	v_cvt_pk_bf16_f32 v1, v16, s0
	ds_write_b16 v180, v1 offset:64
	v_cvt_pk_bf16_f32 v1, v33, s0
	ds_write_b16 v180, v1 offset:144
	v_cvt_pk_bf16_f32 v1, v17, s0
	ds_write_b16 v180, v1 offset:208
	v_cvt_pk_bf16_f32 v1, v34, s0
	ds_write_b16 v180, v1 offset:288
	v_cvt_pk_bf16_f32 v1, v18, s0
	ds_write_b16 v180, v1 offset:352
	v_cvt_pk_bf16_f32 v1, v35, s0
	ds_write_b16 v180, v1 offset:432
	v_cvt_pk_bf16_f32 v1, v19, s0
	ds_write_b16 v180, v1 offset:496
	v_cvt_pk_bf16_f32 v1, v36, s0
	ds_write_b16 v180, v1 offset:1152
	v_cvt_pk_bf16_f32 v1, v20, s0
	ds_write_b16 v180, v1 offset:1216
	v_cvt_pk_bf16_f32 v1, v37, s0
	ds_write_b16 v180, v1 offset:1296
	v_cvt_pk_bf16_f32 v1, v21, s0
	ds_write_b16 v180, v1 offset:1360
	v_cvt_pk_bf16_f32 v1, v38, s0
	ds_write_b16 v180, v1 offset:1440
	v_cvt_pk_bf16_f32 v1, v22, s0
	ds_write_b16 v180, v1 offset:1504
	v_cvt_pk_bf16_f32 v1, v39, s0
	ds_write_b16 v180, v1 offset:1584
	v_cvt_pk_bf16_f32 v1, v23, s0
	ds_write_b16 v180, v1 offset:1648
	v_cvt_pk_bf16_f32 v1, v40, s0
	ds_write_b16 v180, v1 offset:2304
	v_cvt_pk_bf16_f32 v1, v24, s0
	ds_write_b16 v180, v1 offset:2368
	v_cvt_pk_bf16_f32 v1, v41, s0
	ds_write_b16 v180, v1 offset:2448
	v_cvt_pk_bf16_f32 v1, v25, s0
	ds_write_b16 v180, v1 offset:2512
	v_cvt_pk_bf16_f32 v1, v42, s0
	ds_write_b16 v180, v1 offset:2592
	v_cvt_pk_bf16_f32 v1, v26, s0
	ds_write_b16 v180, v1 offset:2656
	v_cvt_pk_bf16_f32 v1, v43, s0
	ds_write_b16 v180, v1 offset:2736
	v_cvt_pk_bf16_f32 v1, v27, s0
	ds_write_b16 v180, v1 offset:2800
	v_cvt_pk_bf16_f32 v1, v44, s0
	ds_write_b16 v180, v1 offset:3456
	v_cvt_pk_bf16_f32 v1, v28, s0
	v_add_co_u32_e32 v12, vcc, s42, v10
	ds_write_b16 v180, v1 offset:3520
	v_cvt_pk_bf16_f32 v1, v45, s0
	v_addc_co_u32_e32 v13, vcc, 0, v11, vcc
	ds_write_b16 v180, v1 offset:3600
	v_cvt_pk_bf16_f32 v1, v29, s0
	s_waitcnt lgkmcnt(14)
	global_store_dwordx4 v[12:13], v[2:5], off sc1
	ds_write_b16 v180, v1 offset:3664
	v_cvt_pk_bf16_f32 v1, v46, s0
	v_add_co_u32_e32 v2, vcc, s91, v10
	ds_write_b16 v180, v1 offset:3744
	s_nop 0
	v_addc_co_u32_e32 v3, vcc, 0, v11, vcc
	v_cvt_pk_bf16_f32 v1, v30, s0
	global_store_dwordx4 v[2:3], v[6:9], off sc1
	ds_write_b16 v180, v1 offset:3808
	v_cvt_pk_bf16_f32 v1, v47, s0
	v_or_b32_e32 v2, s93, v176
	ds_write_b16 v180, v1 offset:3888
	v_cvt_pk_bf16_f32 v1, v31, s0
	v_ashrrev_i32_e32 v3, 31, v2
	ds_write_b16 v180, v1 offset:3952
	v_lshlrev_b64 v[6:7], 11, v[2:3]
	ds_read_b128 v[2:5], v182
	v_lshl_add_u64 v[6:7], s[50:51], 0, v[6:7]
	v_lshl_add_u64 v[6:7], v[6:7], 0, s[72:73]
	v_lshl_add_u64 v[10:11], v[6:7], 0, v[168:169]
	ds_read_b128 v[6:9], v183
	s_waitcnt lgkmcnt(1)
	global_store_dwordx4 v[10:11], v[2:5], off sc1
	s_add_i32 s82, s82, s87
	s_add_i32 s88, s88, s89
	v_add_co_u32_e32 v2, vcc, s90, v10
	s_cmp_lt_i32 s63, s100
	s_nop 0
	v_addc_co_u32_e32 v3, vcc, 0, v11, vcc
	s_waitcnt lgkmcnt(0)
	global_store_dwordx4 v[2:3], v[6:9], off sc1
	ds_read_b128 v[2:5], v183 offset:1152
	ds_read_b128 v[6:9], v183 offset:2304
	v_add_co_u32_e32 v12, vcc, 0x8000, v10
	s_nop 1
	v_addc_co_u32_e32 v13, vcc, 0, v11, vcc
	s_waitcnt lgkmcnt(1)
	global_store_dwordx4 v[12:13], v[2:5], off sc1
	s_nop 1
	v_add_co_u32_e32 v2, vcc, 0xc000, v10
	s_nop 1
	v_addc_co_u32_e32 v3, vcc, 0, v11, vcc
	s_waitcnt lgkmcnt(0)
	global_store_dwordx4 v[2:3], v[6:9], off sc1
	s_cbranch_scc0 .LBB0_749

; __device__ __forceinline__ int lane_id_() { int l; asm volatile("v_mbcnt_lo_u32_b32 %0, -1, 0\n\tv_mbcnt_hi_u32_b32 %0, -1, %0" : "=v"(l)); return l; }
; __device__ __forceinline__ unsigned xb_add(unsigned* p, unsigned v) { return __hip_atomic_fetch_add(p, v, __ATOMIC_RELAXED, __HIP_MEMORY_SCOPE_AGENT); }
; __device__ __forceinline__ void xcd_barrier(const XcdBarrier& b, int wave_s) {
;     asm volatile("s_waitcnt vmcnt(0)" ::: "memory");
;     __syncthreads();
;     if (wave_s == 0 && lane_id_() == 0) {
;         unsigned* bar = b.bar;
;         __builtin_amdgcn_s_waitcnt(0);
;         unsigned nloc = b.st[0], nx = b.st[1];
;         if (nloc == 0u) { xcd_barrier_complete(bar, b.x, nloc, nx); b.st[0] = nloc; b.st[1] = nx; }
;         const unsigned old = xb_add(&bar[XB_XSUB(b.x)], 1u);
;         const unsigned gen = old / nloc;
;         if (old + 1u == (gen + 1u) * nloc) {
;             __builtin_amdgcn_fence(__ATOMIC_RELEASE, "agent");
;             asm volatile("s_waitcnt vmcnt(0)" ::: "memory");
;             const unsigned og = xb_add(&bar[XB_TOP], 1u);
.LBB0_749:
	s_waitcnt vmcnt(0)
	s_and_b64 vcc, exec, s[2:3]
	s_barrier
	s_cbranch_vccnz .LBB0_803
	v_mbcnt_lo_u32_b32 v0, -1, 0
	v_mbcnt_hi_u32_b32 v0, -1, v0
	s_nop 0
	v_cmp_eq_u32_e32 vcc, 0, v0
	s_and_saveexec_b64 s[6:7], vcc
	s_cbranch_execz .LBB0_802
	s_cmp_eq_u32 s101, 1
	s_cbranch_scc0 .Lglob_S5
	s_and_b32 s98, s33, 7
	s_lshl_b32 s99, s98, 2
	s_addk_i32 s99, 0x4800
	v_mov_b32_e32 v3, s99
	s_lshl_b32 s98, s98, 8
	s_addk_i32 s98, 0x4000
	v_mov_b32_e32 v0, s98
	v_mov_b32_e32 v1, 1
	global_atomic_add v2, v0, v1, s[44:45] sc0
	buffer_inv sc1
	s_waitcnt vmcnt(1)
	v_readfirstlane_b32 s98, v2
	s_nop 3
	s_add_u32 s99, s98, 1
	s_and_b32 s99, s99, 31
	s_lshr_b32 s98, s98, 5
	s_cmp_eq_u32 s99, 0
	s_cbranch_scc0 .Llw_S5
	global_atomic_add v3, v1, s[44:45]
	s_branch .Lla_S5

; __device__ __forceinline__ int lane_id_() { int l; asm volatile("v_mbcnt_lo_u32_b32 %0, -1, 0\n\tv_mbcnt_hi_u32_b32 %0, -1, %0" : "=v"(l)); return l; }
; __device__ __forceinline__ unsigned xb_add(unsigned* p, unsigned v) { return __hip_atomic_fetch_add(p, v, __ATOMIC_RELAXED, __HIP_MEMORY_SCOPE_AGENT); }
; __device__ __forceinline__ void xcd_barrier(const XcdBarrier& b, int wave_s) {
;     asm volatile("s_waitcnt vmcnt(0)" ::: "memory");
;     __syncthreads();
;     if (wave_s == 0 && lane_id_() == 0) {
;         unsigned* bar = b.bar;
;         __builtin_amdgcn_s_waitcnt(0);
;         unsigned nloc = b.st[0], nx = b.st[1];
;         if (nloc == 0u) { xcd_barrier_complete(bar, b.x, nloc, nx); b.st[0] = nloc; b.st[1] = nx; }
;         const unsigned old = xb_add(&bar[XB_XSUB(b.x)], 1u);
;         const unsigned gen = old / nloc;
;         if (old + 1u == (gen + 1u) * nloc) {
;             __builtin_amdgcn_fence(__ATOMIC_RELEASE, "agent");
;             asm volatile("s_waitcnt vmcnt(0)" ::: "memory");
;             const unsigned og = xb_add(&bar[XB_TOP], 1u);
.LBB0_1213:
	s_waitcnt vmcnt(0)
	s_and_b64 vcc, exec, s[2:3]
	s_waitcnt lgkmcnt(0)
	s_barrier
	s_cbranch_vccnz .LBB0_1267
	v_mbcnt_lo_u32_b32 v0, -1, 0
	v_mbcnt_hi_u32_b32 v0, -1, v0
	s_nop 0
	v_cmp_eq_u32_e32 vcc, 0, v0
	s_and_saveexec_b64 s[8:9], vcc
	s_cbranch_execz .LBB0_1266
	s_cmp_eq_u32 s101, 1
	s_cbranch_scc0 .Lglob_S8
	s_and_b32 s98, s33, 7
	s_lshl_b32 s99, s98, 2
	s_addk_i32 s99, 0x4800
	v_mov_b32_e32 v3, s99
	s_lshl_b32 s98, s98, 8
	s_addk_i32 s98, 0x4000
	v_mov_b32_e32 v0, s98
	v_mov_b32_e32 v1, 1
	global_atomic_add v2, v0, v1, s[44:45] sc0
	buffer_inv sc1
	s_waitcnt vmcnt(1)
	v_readfirstlane_b32 s98, v2
	s_nop 3
	s_add_u32 s99, s98, 1
	s_and_b32 s99, s99, 31
	s_lshr_b32 s98, s98, 5
	s_cmp_eq_u32 s99, 0
	s_cbranch_scc0 .Llw_S8
	global_atomic_add v3, v1, s[44:45]
	s_branch .Lla_S8

; __device__ __forceinline__ int lane_id_() { int l; asm volatile("v_mbcnt_lo_u32_b32 %0, -1, 0\n\tv_mbcnt_hi_u32_b32 %0, -1, %0" : "=v"(l)); return l; }
; __device__ __forceinline__ unsigned xb_add(unsigned* p, unsigned v) { return __hip_atomic_fetch_add(p, v, __ATOMIC_RELAXED, __HIP_MEMORY_SCOPE_AGENT); }
; __device__ __forceinline__ void xcd_barrier(const XcdBarrier& b, int wave_s) {
;     asm volatile("s_waitcnt vmcnt(0)" ::: "memory");
;     __syncthreads();
;     if (wave_s == 0 && lane_id_() == 0) {
;         unsigned* bar = b.bar;
;         __builtin_amdgcn_s_waitcnt(0);
;         unsigned nloc = b.st[0], nx = b.st[1];
;         if (nloc == 0u) { xcd_barrier_complete(bar, b.x, nloc, nx); b.st[0] = nloc; b.st[1] = nx; }
;         const unsigned old = xb_add(&bar[XB_XSUB(b.x)], 1u);
;         const unsigned gen = old / nloc;
;         if (old + 1u == (gen + 1u) * nloc) {
;             __builtin_amdgcn_fence(__ATOMIC_RELEASE, "agent");
;             asm volatile("s_waitcnt vmcnt(0)" ::: "memory");
;             const unsigned og = xb_add(&bar[XB_TOP], 1u);
.LBB0_1589:
	s_waitcnt vmcnt(0)
	s_and_b64 vcc, exec, s[2:3]
	s_waitcnt vmcnt(0)
	s_barrier
	s_cbranch_vccnz .LBB0_1643
	v_mbcnt_lo_u32_b32 v0, -1, 0
	v_mbcnt_hi_u32_b32 v0, -1, v0
	s_nop 0
	v_cmp_eq_u32_e32 vcc, 0, v0
	s_and_saveexec_b64 s[8:9], vcc
	s_cbranch_execz .LBB0_1642
	s_cmp_eq_u32 s101, 1
	s_cbranch_scc0 .Lglob_S9
	s_and_b32 s98, s33, 7
	s_lshl_b32 s99, s98, 2
	s_addk_i32 s99, 0x4800
	v_mov_b32_e32 v3, s99
	s_lshl_b32 s98, s98, 8
	s_addk_i32 s98, 0x4000
	v_mov_b32_e32 v0, s98
	v_mov_b32_e32 v1, 1
	global_atomic_add v2, v0, v1, s[44:45] sc0
	buffer_inv sc1
	s_waitcnt vmcnt(1)
	v_readfirstlane_b32 s98, v2
	s_nop 3
	s_add_u32 s99, s98, 1
	s_and_b32 s99, s99, 31
	s_lshr_b32 s98, s98, 5
	s_cmp_eq_u32 s99, 0
	s_cbranch_scc0 .Llw_S9
	global_atomic_add v3, v1, s[44:45]
	s_branch .Lla_S9

; #define PG8_LAS __attribute__((address_space(3)))
; __device__ __forceinline__ unsigned pk_bf16(float lo, float hi) { typedef __bf16 b2_t __attribute__((ext_vector_type(2))); f32x2 v = {lo, hi}; b2_t b = __builtin_convertvector(v, b2_t); return __builtin_bit_cast(unsigned, b); }
; __device__ __forceinline__ float fast_sigmoid(float v) { return __builtin_amdgcn_rcpf(1.0f + __builtin_amdgcn_exp2f(-1.44269504089f * v)); }
;     __device__ __forceinline__ void operator()(const f32x4 (&acc)[2][2][4][2], const Unit& u, int wr, int wc, int fr, int fq, PG8_LAS unsigned char* lds, int wid) const {
;         const int t = u.pn >> 2; bf16_t* basep = O + (size_t)t * split_stride;
;         const int row0 = u.pm * BM + wr * 64 + fr, col0 = (u.pn & 3) * BM + wc * 32 + 8 * fq;
;         const bool act = t >= GELU_FROM;
; #pragma unroll
;         for (int ai = 0; ai < 2; ++ai)
; #pragma unroll
;             for (int m = 0; m < 4; ++m) {
;                 const float rstd = __builtin_amdgcn_rsqf(*(const PG8_LAS float*)(lds + PRE_SLOT + wid * 512 + (m & 1) * 256 + (fr + 16 * ((ai * 4 + m) >> 1)) * 4) * (1.0f / 1024.0f) + 1e-6f);
; #pragma unroll
;                 for (int bj = 0; bj < 2; ++bj) {
;                     float h[8];
; #pragma unroll
;                     for (int n = 0; n < 2; ++n)
; #pragma unroll
;                         for (int j = 0; j < 4; ++j) { float v = acc[ai][bj][m][n][j] * rstd;
;                             if (act) { const float z = 1.5957691216f * (v + 0.044715f * v * v * v); v = v * fast_sigmoid(z); }
;                             h[4 * n + j] = v; }
;                     u32x4 w; w.x = pk_bf16(h[0], h[1]); w.y = pk_bf16(h[2], h[3]); w.z = pk_bf16(h[4], h[5]); w.w = pk_bf16(h[6], h[7]);
;                     *(u32x4*)(basep + (size_t)(row0 + ai * HALF + m * 16) * 1024 + col0 + bj * HALF) = w;
.LBB0_1783:
	s_ashr_i32 s41, s40, 31
	s_lshl_b64 s[6:7], s[40:41], 25
	s_add_u32 s6, s50, s6
	s_addc_u32 s7, s51, s7
	v_lshl_add_u32 v2, s36, 8, v144
	s_lshl_b32 s36, s38, 8
	s_and_b32 s36, s36, 0x300
	v_or_b32_e32 v0, s36, v147
	v_lshlrev_b32_e32 v0, 1, v0
	v_ashrrev_i32_e32 v3, 31, v2
	v_lshl_add_u64 v[124:125], s[6:7], 0, v[0:1]
	v_lshlrev_b64 v[126:127], 11, v[2:3]
	v_lshl_add_u64 v[126:127], v[124:125], 0, v[126:127]
	v_cvt_pk_bf16_f32 v128, v128, v129
	v_cvt_pk_bf16_f32 v129, v130, v131
	v_cvt_pk_bf16_f32 v130, v156, v157
	v_cvt_pk_bf16_f32 v131, v158, v159
	s_and_b64 vcc, exec, s[10:11]
	v_mul_f32_e32 v0, v120, v155
	global_store_dwordx4 v[126:127], v[128:131], off sc1
	s_cbranch_vccnz .LBB0_1785
	v_mul_f32_e32 v120, 0x3d372713, v0
	v_mul_f32_e32 v120, v0, v120
	v_fma_f32 v120, v0, v120, v0
	v_mul_f32_e32 v120, 0x3fcc422a, v120
	v_mul_f32_e32 v120, 0xbfb8aa3b, v120
	v_exp_f32_e32 v120, v120
	s_nop 0
	v_add_f32_e32 v120, 1.0, v120
	v_rcp_f32_e32 v120, v120
	s_nop 0
	v_mul_f32_e32 v0, v0, v120

; #define PG8_LAS __attribute__((address_space(3)))
; __device__ __forceinline__ unsigned pk_bf16(float lo, float hi) { typedef __bf16 b2_t __attribute__((ext_vector_type(2))); f32x2 v = {lo, hi}; b2_t b = __builtin_convertvector(v, b2_t); return __builtin_bit_cast(unsigned, b); }
; __device__ __forceinline__ float fast_sigmoid(float v) { return __builtin_amdgcn_rcpf(1.0f + __builtin_amdgcn_exp2f(-1.44269504089f * v)); }
;     __device__ __forceinline__ void operator()(const f32x4 (&acc)[2][2][4][2], const Unit& u, int wr, int wc, int fr, int fq, PG8_LAS unsigned char* lds, int wid) const {
;     ...
;                 const float rstd = __builtin_amdgcn_rsqf(*(const PG8_LAS float*)(lds + PRE_SLOT + wid * 512 + (m & 1) * 256 + (fr + 16 * ((ai * 4 + m) >> 1)) * 4) * (1.0f / 1024.0f) + 1e-6f);
; #pragma unroll
;                 for (int bj = 0; bj < 2; ++bj) {
;                     float h[8];
; #pragma unroll
;                     for (int n = 0; n < 2; ++n)
; #pragma unroll
;                         for (int j = 0; j < 4; ++j) { float v = acc[ai][bj][m][n][j] * rstd;
;                             if (act) { const float z = 1.5957691216f * (v + 0.044715f * v * v * v); v = v * fast_sigmoid(z); }
;                             h[4 * n + j] = v; }
;                     u32x4 w; w.x = pk_bf16(h[0], h[1]); w.y = pk_bf16(h[2], h[3]); w.z = pk_bf16(h[4], h[5]); w.w = pk_bf16(h[6], h[7]);
;                     *(u32x4*)(basep + (size_t)(row0 + ai * HALF + m * 16) * 1024 + col0 + bj * HALF) = w;
.LBB0_1799:
	ds_read_b32 v123, v154 offset:256
	v_cvt_pk_bf16_f32 v120, v0, v120
	v_cvt_pk_bf16_f32 v121, v121, v122
	v_cvt_pk_bf16_f32 v122, v116, v117
	s_and_b64 vcc, exec, s[10:11]
	s_waitcnt lgkmcnt(0)
	v_fmamk_f32 v0, v123, 0x3a800000, v148
	v_rsq_f32_e32 v0, v0
	v_cvt_pk_bf16_f32 v123, v118, v119
	global_store_dwordx4 v[126:127], v[120:123], off offset:256 sc1
	v_mul_f32_e32 v112, v112, v0
	s_cbranch_vccnz .LBB0_1801
	v_mul_f32_e32 v116, 0x3d372713, v112
	v_mul_f32_e32 v116, v112, v116
	v_fma_f32 v116, v112, v116, v112
	v_mul_f32_e32 v116, 0x3fcc422a, v116
	v_mul_f32_e32 v116, 0xbfb8aa3b, v116
	v_exp_f32_e32 v116, v116
	s_nop 0
	v_add_f32_e32 v116, 1.0, v116
	v_rcp_f32_e32 v116, v116
	s_nop 0
	v_mul_f32_e32 v112, v112, v116

; #define PG8_LAS __attribute__((address_space(3)))
; __device__ __forceinline__ unsigned pk_bf16(float lo, float hi) { typedef __bf16 b2_t __attribute__((ext_vector_type(2))); f32x2 v = {lo, hi}; b2_t b = __builtin_convertvector(v, b2_t); return __builtin_bit_cast(unsigned, b); }
; __device__ __forceinline__ float fast_sigmoid(float v) { return __builtin_amdgcn_rcpf(1.0f + __builtin_amdgcn_exp2f(-1.44269504089f * v)); }
;     __device__ __forceinline__ void operator()(const f32x4 (&acc)[2][2][4][2], const Unit& u, int wr, int wc, int fr, int fq, PG8_LAS unsigned char* lds, int wid) const {
;     ...
;                 const float rstd = __builtin_amdgcn_rsqf(*(const PG8_LAS float*)(lds + PRE_SLOT + wid * 512 + (m & 1) * 256 + (fr + 16 * ((ai * 4 + m) >> 1)) * 4) * (1.0f / 1024.0f) + 1e-6f);
; #pragma unroll
;                 for (int bj = 0; bj < 2; ++bj) {
;                     float h[8];
; #pragma unroll
;                     for (int n = 0; n < 2; ++n)
; #pragma unroll
;                         for (int j = 0; j < 4; ++j) { float v = acc[ai][bj][m][n][j] * rstd;
;                             if (act) { const float z = 1.5957691216f * (v + 0.044715f * v * v * v); v = v * fast_sigmoid(z); }
;                             h[4 * n + j] = v; }
;                     u32x4 w; w.x = pk_bf16(h[0], h[1]); w.y = pk_bf16(h[2], h[3]); w.z = pk_bf16(h[4], h[5]); w.w = pk_bf16(h[6], h[7]);
;                     *(u32x4*)(basep + (size_t)(row0 + ai * HALF + m * 16) * 1024 + col0 + bj * HALF) = w;
.LBB0_1815:
	v_or_b32_e32 v108, 16, v2
	v_ashrrev_i32_e32 v109, 31, v108
	v_lshlrev_b64 v[108:109], 11, v[108:109]
	v_lshl_add_u64 v[108:109], v[124:125], 0, v[108:109]
	v_cvt_pk_bf16_f32 v112, v112, v113
	v_cvt_pk_bf16_f32 v113, v114, v115
	v_cvt_pk_bf16_f32 v114, v116, v117
	v_cvt_pk_bf16_f32 v115, v110, v111
	s_and_b64 vcc, exec, s[10:11]
	v_mul_f32_e32 v104, v104, v0
	global_store_dwordx4 v[108:109], v[112:115], off sc1
	s_cbranch_vccnz .LBB0_1817
	v_mul_f32_e32 v110, 0x3d372713, v104
	v_mul_f32_e32 v110, v104, v110
	v_fma_f32 v110, v104, v110, v104
	v_mul_f32_e32 v110, 0x3fcc422a, v110
	v_mul_f32_e32 v110, 0xbfb8aa3b, v110
	v_exp_f32_e32 v110, v110
	s_nop 0
	v_add_f32_e32 v110, 1.0, v110
	v_rcp_f32_e32 v110, v110
	s_nop 0
	v_mul_f32_e32 v104, v104, v110

; #define PG8_LAS __attribute__((address_space(3)))
; __device__ __forceinline__ unsigned pk_bf16(float lo, float hi) { typedef __bf16 b2_t __attribute__((ext_vector_type(2))); f32x2 v = {lo, hi}; b2_t b = __builtin_convertvector(v, b2_t); return __builtin_bit_cast(unsigned, b); }
; __device__ __forceinline__ float fast_sigmoid(float v) { return __builtin_amdgcn_rcpf(1.0f + __builtin_amdgcn_exp2f(-1.44269504089f * v)); }
;     __device__ __forceinline__ void operator()(const f32x4 (&acc)[2][2][4][2], const Unit& u, int wr, int wc, int fr, int fq, PG8_LAS unsigned char* lds, int wid) const {
;     ...
;                 const float rstd = __builtin_amdgcn_rsqf(*(const PG8_LAS float*)(lds + PRE_SLOT + wid * 512 + (m & 1) * 256 + (fr + 16 * ((ai * 4 + m) >> 1)) * 4) * (1.0f / 1024.0f) + 1e-6f);
; #pragma unroll
;                 for (int bj = 0; bj < 2; ++bj) {
;                     float h[8];
; #pragma unroll
;                     for (int n = 0; n < 2; ++n)
; #pragma unroll
;                         for (int j = 0; j < 4; ++j) { float v = acc[ai][bj][m][n][j] * rstd;
;                             if (act) { const float z = 1.5957691216f * (v + 0.044715f * v * v * v); v = v * fast_sigmoid(z); }
;                             h[4 * n + j] = v; }
;                     u32x4 w; w.x = pk_bf16(h[0], h[1]); w.y = pk_bf16(h[2], h[3]); w.z = pk_bf16(h[4], h[5]); w.w = pk_bf16(h[6], h[7]);
;                     *(u32x4*)(basep + (size_t)(row0 + ai * HALF + m * 16) * 1024 + col0 + bj * HALF) = w;
.LBB0_1831:
	ds_read_b32 v0, v154 offset:64
	v_cvt_pk_bf16_f32 v104, v104, v105
	v_cvt_pk_bf16_f32 v105, v106, v107
	v_cvt_pk_bf16_f32 v106, v100, v101
	v_cvt_pk_bf16_f32 v107, v102, v103
	s_waitcnt lgkmcnt(0)
	v_fmamk_f32 v0, v0, 0x3a800000, v148
	v_rsq_f32_e32 v0, v0
	s_and_b64 vcc, exec, s[10:11]
	global_store_dwordx4 v[108:109], v[104:107], off offset:256 sc1
	v_mul_f32_e32 v96, v96, v0
	s_cbranch_vccnz .LBB0_1833
	v_mul_f32_e32 v100, 0x3d372713, v96
	v_mul_f32_e32 v100, v96, v100
	v_fma_f32 v100, v96, v100, v96
	v_mul_f32_e32 v100, 0x3fcc422a, v100
	v_mul_f32_e32 v100, 0xbfb8aa3b, v100
	v_exp_f32_e32 v100, v100
	s_nop 0
	v_add_f32_e32 v100, 1.0, v100
	v_rcp_f32_e32 v100, v100
	s_nop 0
	v_mul_f32_e32 v96, v96, v100

; #define PG8_LAS __attribute__((address_space(3)))
; __device__ __forceinline__ unsigned pk_bf16(float lo, float hi) { typedef __bf16 b2_t __attribute__((ext_vector_type(2))); f32x2 v = {lo, hi}; b2_t b = __builtin_convertvector(v, b2_t); return __builtin_bit_cast(unsigned, b); }
; __device__ __forceinline__ float fast_sigmoid(float v) { return __builtin_amdgcn_rcpf(1.0f + __builtin_amdgcn_exp2f(-1.44269504089f * v)); }
;     __device__ __forceinline__ void operator()(const f32x4 (&acc)[2][2][4][2], const Unit& u, int wr, int wc, int fr, int fq, PG8_LAS unsigned char* lds, int wid) const {
;     ...
;                 const float rstd = __builtin_amdgcn_rsqf(*(const PG8_LAS float*)(lds + PRE_SLOT + wid * 512 + (m & 1) * 256 + (fr + 16 * ((ai * 4 + m) >> 1)) * 4) * (1.0f / 1024.0f) + 1e-6f);
; #pragma unroll
;                 for (int bj = 0; bj < 2; ++bj) {
;                     float h[8];
; #pragma unroll
;                     for (int n = 0; n < 2; ++n)
; #pragma unroll
;                         for (int j = 0; j < 4; ++j) { float v = acc[ai][bj][m][n][j] * rstd;
;                             if (act) { const float z = 1.5957691216f * (v + 0.044715f * v * v * v); v = v * fast_sigmoid(z); }
;                             h[4 * n + j] = v; }
;                     u32x4 w; w.x = pk_bf16(h[0], h[1]); w.y = pk_bf16(h[2], h[3]); w.z = pk_bf16(h[4], h[5]); w.w = pk_bf16(h[6], h[7]);
;                     *(u32x4*)(basep + (size_t)(row0 + ai * HALF + m * 16) * 1024 + col0 + bj * HALF) = w;
.LBB0_1847:
	v_or_b32_e32 v92, 32, v2
	v_ashrrev_i32_e32 v93, 31, v92
	v_lshlrev_b64 v[92:93], 11, v[92:93]
	v_lshl_add_u64 v[92:93], v[124:125], 0, v[92:93]
	v_cvt_pk_bf16_f32 v96, v96, v97
	v_cvt_pk_bf16_f32 v97, v98, v99
	v_cvt_pk_bf16_f32 v98, v100, v101
	v_cvt_pk_bf16_f32 v99, v94, v95
	s_and_b64 vcc, exec, s[10:11]
	v_mul_f32_e32 v88, v88, v0
	global_store_dwordx4 v[92:93], v[96:99], off sc1
	s_cbranch_vccnz .LBB0_1849
	v_mul_f32_e32 v94, 0x3d372713, v88
	v_mul_f32_e32 v94, v88, v94
	v_fma_f32 v94, v88, v94, v88
	v_mul_f32_e32 v94, 0x3fcc422a, v94
	v_mul_f32_e32 v94, 0xbfb8aa3b, v94
	v_exp_f32_e32 v94, v94
	s_nop 0
	v_add_f32_e32 v94, 1.0, v94
	v_rcp_f32_e32 v94, v94
	s_nop 0
	v_mul_f32_e32 v88, v88, v94

; #define PG8_LAS __attribute__((address_space(3)))
; __device__ __forceinline__ unsigned pk_bf16(float lo, float hi) { typedef __bf16 b2_t __attribute__((ext_vector_type(2))); f32x2 v = {lo, hi}; b2_t b = __builtin_convertvector(v, b2_t); return __builtin_bit_cast(unsigned, b); }
; __device__ __forceinline__ float fast_sigmoid(float v) { return __builtin_amdgcn_rcpf(1.0f + __builtin_amdgcn_exp2f(-1.44269504089f * v)); }
;     __device__ __forceinline__ void operator()(const f32x4 (&acc)[2][2][4][2], const Unit& u, int wr, int wc, int fr, int fq, PG8_LAS unsigned char* lds, int wid) const {
;     ...
;                 const float rstd = __builtin_amdgcn_rsqf(*(const PG8_LAS float*)(lds + PRE_SLOT + wid * 512 + (m & 1) * 256 + (fr + 16 * ((ai * 4 + m) >> 1)) * 4) * (1.0f / 1024.0f) + 1e-6f);
; #pragma unroll
;                 for (int bj = 0; bj < 2; ++bj) {
;                     float h[8];
; #pragma unroll
;                     for (int n = 0; n < 2; ++n)
; #pragma unroll
;                         for (int j = 0; j < 4; ++j) { float v = acc[ai][bj][m][n][j] * rstd;
;                             if (act) { const float z = 1.5957691216f * (v + 0.044715f * v * v * v); v = v * fast_sigmoid(z); }
;                             h[4 * n + j] = v; }
;                     u32x4 w; w.x = pk_bf16(h[0], h[1]); w.y = pk_bf16(h[2], h[3]); w.z = pk_bf16(h[4], h[5]); w.w = pk_bf16(h[6], h[7]);
;                     *(u32x4*)(basep + (size_t)(row0 + ai * HALF + m * 16) * 1024 + col0 + bj * HALF) = w;
.LBB0_1863:
	ds_read_b32 v0, v154 offset:320
	v_cvt_pk_bf16_f32 v88, v88, v89
	v_cvt_pk_bf16_f32 v89, v90, v91
	v_cvt_pk_bf16_f32 v90, v84, v85
	v_cvt_pk_bf16_f32 v91, v86, v87
	s_waitcnt lgkmcnt(0)
	v_fmamk_f32 v0, v0, 0x3a800000, v148
	v_rsq_f32_e32 v0, v0
	s_and_b64 vcc, exec, s[10:11]
	global_store_dwordx4 v[92:93], v[88:91], off offset:256 sc1
	v_mul_f32_e32 v80, v80, v0
	s_cbranch_vccnz .LBB0_1865
	v_mul_f32_e32 v84, 0x3d372713, v80
	v_mul_f32_e32 v84, v80, v84
	v_fma_f32 v84, v80, v84, v80
	v_mul_f32_e32 v84, 0x3fcc422a, v84
	v_mul_f32_e32 v84, 0xbfb8aa3b, v84
	v_exp_f32_e32 v84, v84
	s_nop 0
	v_add_f32_e32 v84, 1.0, v84
	v_rcp_f32_e32 v84, v84
	s_nop 0
	v_mul_f32_e32 v80, v80, v84

; #define PG8_LAS __attribute__((address_space(3)))
; __device__ __forceinline__ unsigned pk_bf16(float lo, float hi) { typedef __bf16 b2_t __attribute__((ext_vector_type(2))); f32x2 v = {lo, hi}; b2_t b = __builtin_convertvector(v, b2_t); return __builtin_bit_cast(unsigned, b); }
; __device__ __forceinline__ float fast_sigmoid(float v) { return __builtin_amdgcn_rcpf(1.0f + __builtin_amdgcn_exp2f(-1.44269504089f * v)); }
;     __device__ __forceinline__ void operator()(const f32x4 (&acc)[2][2][4][2], const Unit& u, int wr, int wc, int fr, int fq, PG8_LAS unsigned char* lds, int wid) const {
;     ...
;                 const float rstd = __builtin_amdgcn_rsqf(*(const PG8_LAS float*)(lds + PRE_SLOT + wid * 512 + (m & 1) * 256 + (fr + 16 * ((ai * 4 + m) >> 1)) * 4) * (1.0f / 1024.0f) + 1e-6f);
; #pragma unroll
;                 for (int bj = 0; bj < 2; ++bj) {
;                     float h[8];
; #pragma unroll
;                     for (int n = 0; n < 2; ++n)
; #pragma unroll
;                         for (int j = 0; j < 4; ++j) { float v = acc[ai][bj][m][n][j] * rstd;
;                             if (act) { const float z = 1.5957691216f * (v + 0.044715f * v * v * v); v = v * fast_sigmoid(z); }
;                             h[4 * n + j] = v; }
;                     u32x4 w; w.x = pk_bf16(h[0], h[1]); w.y = pk_bf16(h[2], h[3]); w.z = pk_bf16(h[4], h[5]); w.w = pk_bf16(h[6], h[7]);
;                     *(u32x4*)(basep + (size_t)(row0 + ai * HALF + m * 16) * 1024 + col0 + bj * HALF) = w;
.LBB0_1879:
	v_or_b32_e32 v76, 48, v2
	v_ashrrev_i32_e32 v77, 31, v76
	v_lshlrev_b64 v[76:77], 11, v[76:77]
	v_lshl_add_u64 v[76:77], v[124:125], 0, v[76:77]
	v_cvt_pk_bf16_f32 v80, v80, v81
	v_cvt_pk_bf16_f32 v81, v82, v83
	v_cvt_pk_bf16_f32 v82, v84, v85
	v_cvt_pk_bf16_f32 v83, v78, v79
	s_and_b64 vcc, exec, s[10:11]
	v_mul_f32_e32 v72, v72, v0
	global_store_dwordx4 v[76:77], v[80:83], off sc1
	s_cbranch_vccnz .LBB0_1881
	v_mul_f32_e32 v78, 0x3d372713, v72
	v_mul_f32_e32 v78, v72, v78
	v_fma_f32 v78, v72, v78, v72
	v_mul_f32_e32 v78, 0x3fcc422a, v78
	v_mul_f32_e32 v78, 0xbfb8aa3b, v78
	v_exp_f32_e32 v78, v78
	s_nop 0
	v_add_f32_e32 v78, 1.0, v78
	v_rcp_f32_e32 v78, v78
	s_nop 0
	v_mul_f32_e32 v72, v72, v78

; #define PG8_LAS __attribute__((address_space(3)))
; __device__ __forceinline__ unsigned pk_bf16(float lo, float hi) { typedef __bf16 b2_t __attribute__((ext_vector_type(2))); f32x2 v = {lo, hi}; b2_t b = __builtin_convertvector(v, b2_t); return __builtin_bit_cast(unsigned, b); }
; __device__ __forceinline__ float fast_sigmoid(float v) { return __builtin_amdgcn_rcpf(1.0f + __builtin_amdgcn_exp2f(-1.44269504089f * v)); }
;     __device__ __forceinline__ void operator()(const f32x4 (&acc)[2][2][4][2], const Unit& u, int wr, int wc, int fr, int fq, PG8_LAS unsigned char* lds, int wid) const {
;     ...
;                 const float rstd = __builtin_amdgcn_rsqf(*(const PG8_LAS float*)(lds + PRE_SLOT + wid * 512 + (m & 1) * 256 + (fr + 16 * ((ai * 4 + m) >> 1)) * 4) * (1.0f / 1024.0f) + 1e-6f);
; #pragma unroll
;                 for (int bj = 0; bj < 2; ++bj) {
;                     float h[8];
; #pragma unroll
;                     for (int n = 0; n < 2; ++n)
; #pragma unroll
;                         for (int j = 0; j < 4; ++j) { float v = acc[ai][bj][m][n][j] * rstd;
;                             if (act) { const float z = 1.5957691216f * (v + 0.044715f * v * v * v); v = v * fast_sigmoid(z); }
;                             h[4 * n + j] = v; }
;                     u32x4 w; w.x = pk_bf16(h[0], h[1]); w.y = pk_bf16(h[2], h[3]); w.z = pk_bf16(h[4], h[5]); w.w = pk_bf16(h[6], h[7]);
;                     *(u32x4*)(basep + (size_t)(row0 + ai * HALF + m * 16) * 1024 + col0 + bj * HALF) = w;
.LBB0_1895:
	ds_read_b32 v0, v154 offset:128
	v_cvt_pk_bf16_f32 v72, v72, v73
	v_cvt_pk_bf16_f32 v73, v74, v75
	v_cvt_pk_bf16_f32 v74, v68, v69
	v_cvt_pk_bf16_f32 v75, v70, v71
	s_waitcnt lgkmcnt(0)
	v_fmamk_f32 v0, v0, 0x3a800000, v148
	v_rsq_f32_e32 v0, v0
	s_and_b64 vcc, exec, s[10:11]
	global_store_dwordx4 v[76:77], v[72:75], off offset:256 sc1
	v_mul_f32_e32 v64, v64, v0
	s_cbranch_vccnz .LBB0_1897
	v_mul_f32_e32 v68, 0x3d372713, v64
	v_mul_f32_e32 v68, v64, v68
	v_fma_f32 v68, v64, v68, v64
	v_mul_f32_e32 v68, 0x3fcc422a, v68
	v_mul_f32_e32 v68, 0xbfb8aa3b, v68
	v_exp_f32_e32 v68, v68
	s_nop 0
	v_add_f32_e32 v68, 1.0, v68
	v_rcp_f32_e32 v68, v68
	s_nop 0
	v_mul_f32_e32 v64, v64, v68

; #define PG8_LAS __attribute__((address_space(3)))
; __device__ __forceinline__ unsigned pk_bf16(float lo, float hi) { typedef __bf16 b2_t __attribute__((ext_vector_type(2))); f32x2 v = {lo, hi}; b2_t b = __builtin_convertvector(v, b2_t); return __builtin_bit_cast(unsigned, b); }
; __device__ __forceinline__ float fast_sigmoid(float v) { return __builtin_amdgcn_rcpf(1.0f + __builtin_amdgcn_exp2f(-1.44269504089f * v)); }
;     __device__ __forceinline__ void operator()(const f32x4 (&acc)[2][2][4][2], const Unit& u, int wr, int wc, int fr, int fq, PG8_LAS unsigned char* lds, int wid) const {
;     ...
;                 const float rstd = __builtin_amdgcn_rsqf(*(const PG8_LAS float*)(lds + PRE_SLOT + wid * 512 + (m & 1) * 256 + (fr + 16 * ((ai * 4 + m) >> 1)) * 4) * (1.0f / 1024.0f) + 1e-6f);
; #pragma unroll
;                 for (int bj = 0; bj < 2; ++bj) {
;                     float h[8];
; #pragma unroll
;                     for (int n = 0; n < 2; ++n)
; #pragma unroll
;                         for (int j = 0; j < 4; ++j) { float v = acc[ai][bj][m][n][j] * rstd;
;                             if (act) { const float z = 1.5957691216f * (v + 0.044715f * v * v * v); v = v * fast_sigmoid(z); }
;                             h[4 * n + j] = v; }
;                     u32x4 w; w.x = pk_bf16(h[0], h[1]); w.y = pk_bf16(h[2], h[3]); w.z = pk_bf16(h[4], h[5]); w.w = pk_bf16(h[6], h[7]);
;                     *(u32x4*)(basep + (size_t)(row0 + ai * HALF + m * 16) * 1024 + col0 + bj * HALF) = w;
.LBB0_1911:
	v_lshlrev_b64 v[60:61], 11, v[2:3]
	v_lshl_add_u64 v[60:61], v[124:125], 0, v[60:61]
	v_cvt_pk_bf16_f32 v64, v64, v65
	v_cvt_pk_bf16_f32 v65, v66, v67
	v_cvt_pk_bf16_f32 v67, v62, v63
	v_add_co_u32_e32 v62, vcc, 0x40000, v60
	v_cvt_pk_bf16_f32 v66, v68, v69
	s_nop 0
	v_addc_co_u32_e32 v63, vcc, 0, v61, vcc
	s_and_b64 vcc, exec, s[10:11]
	v_mul_f32_e32 v56, v56, v0
	global_store_dwordx4 v[62:63], v[64:67], off sc1
	s_cbranch_vccnz .LBB0_1913
	v_mul_f32_e32 v62, 0x3d372713, v56
	v_mul_f32_e32 v62, v56, v62
	v_fma_f32 v62, v56, v62, v56
	v_mul_f32_e32 v62, 0x3fcc422a, v62
	v_mul_f32_e32 v62, 0xbfb8aa3b, v62
	v_exp_f32_e32 v62, v62
	s_nop 0
	v_add_f32_e32 v62, 1.0, v62
	v_rcp_f32_e32 v62, v62
	s_nop 0
	v_mul_f32_e32 v56, v56, v62

; #define PG8_LAS __attribute__((address_space(3)))
; __device__ __forceinline__ unsigned pk_bf16(float lo, float hi) { typedef __bf16 b2_t __attribute__((ext_vector_type(2))); f32x2 v = {lo, hi}; b2_t b = __builtin_convertvector(v, b2_t); return __builtin_bit_cast(unsigned, b); }
; __device__ __forceinline__ float fast_sigmoid(float v) { return __builtin_amdgcn_rcpf(1.0f + __builtin_amdgcn_exp2f(-1.44269504089f * v)); }
;     __device__ __forceinline__ void operator()(const f32x4 (&acc)[2][2][4][2], const Unit& u, int wr, int wc, int fr, int fq, PG8_LAS unsigned char* lds, int wid) const {
;     ...
;                 const float rstd = __builtin_amdgcn_rsqf(*(const PG8_LAS float*)(lds + PRE_SLOT + wid * 512 + (m & 1) * 256 + (fr + 16 * ((ai * 4 + m) >> 1)) * 4) * (1.0f / 1024.0f) + 1e-6f);
; #pragma unroll
;                 for (int bj = 0; bj < 2; ++bj) {
;                     float h[8];
; #pragma unroll
;                     for (int n = 0; n < 2; ++n)
; #pragma unroll
;                         for (int j = 0; j < 4; ++j) { float v = acc[ai][bj][m][n][j] * rstd;
;                             if (act) { const float z = 1.5957691216f * (v + 0.044715f * v * v * v); v = v * fast_sigmoid(z); }
;                             h[4 * n + j] = v; }
;                     u32x4 w; w.x = pk_bf16(h[0], h[1]); w.y = pk_bf16(h[2], h[3]); w.z = pk_bf16(h[4], h[5]); w.w = pk_bf16(h[6], h[7]);
;                     *(u32x4*)(basep + (size_t)(row0 + ai * HALF + m * 16) * 1024 + col0 + bj * HALF) = w;
.LBB0_1927:
	ds_read_b32 v0, v154 offset:384
	v_lshl_add_u64 v[60:61], v[60:61], 0, s[14:15]
	v_cvt_pk_bf16_f32 v56, v56, v57
	v_cvt_pk_bf16_f32 v57, v58, v59
	v_cvt_pk_bf16_f32 v58, v52, v53
	s_waitcnt lgkmcnt(0)
	v_fmamk_f32 v0, v0, 0x3a800000, v148
	v_rsq_f32_e32 v0, v0
	v_cvt_pk_bf16_f32 v59, v54, v55
	s_and_b64 vcc, exec, s[10:11]
	global_store_dwordx4 v[60:61], v[56:59], off offset:256 sc1
	v_mul_f32_e32 v48, v48, v0
	s_cbranch_vccnz .LBB0_1929
	v_mul_f32_e32 v52, 0x3d372713, v48
	v_mul_f32_e32 v52, v48, v52
	v_fma_f32 v52, v48, v52, v48
	v_mul_f32_e32 v52, 0x3fcc422a, v52
	v_mul_f32_e32 v52, 0xbfb8aa3b, v52
	v_exp_f32_e32 v52, v52
	s_nop 0
	v_add_f32_e32 v52, 1.0, v52
	v_rcp_f32_e32 v52, v52
	s_nop 0
	v_mul_f32_e32 v48, v48, v52

; #define PG8_LAS __attribute__((address_space(3)))
; __device__ __forceinline__ unsigned pk_bf16(float lo, float hi) { typedef __bf16 b2_t __attribute__((ext_vector_type(2))); f32x2 v = {lo, hi}; b2_t b = __builtin_convertvector(v, b2_t); return __builtin_bit_cast(unsigned, b); }
; __device__ __forceinline__ float fast_sigmoid(float v) { return __builtin_amdgcn_rcpf(1.0f + __builtin_amdgcn_exp2f(-1.44269504089f * v)); }
;     __device__ __forceinline__ void operator()(const f32x4 (&acc)[2][2][4][2], const Unit& u, int wr, int wc, int fr, int fq, PG8_LAS unsigned char* lds, int wid) const {
;     ...
;                 const float rstd = __builtin_amdgcn_rsqf(*(const PG8_LAS float*)(lds + PRE_SLOT + wid * 512 + (m & 1) * 256 + (fr + 16 * ((ai * 4 + m) >> 1)) * 4) * (1.0f / 1024.0f) + 1e-6f);
; #pragma unroll
;                 for (int bj = 0; bj < 2; ++bj) {
;                     float h[8];
; #pragma unroll
;                     for (int n = 0; n < 2; ++n)
; #pragma unroll
;                         for (int j = 0; j < 4; ++j) { float v = acc[ai][bj][m][n][j] * rstd;
;                             if (act) { const float z = 1.5957691216f * (v + 0.044715f * v * v * v); v = v * fast_sigmoid(z); }
;                             h[4 * n + j] = v; }
;                     u32x4 w; w.x = pk_bf16(h[0], h[1]); w.y = pk_bf16(h[2], h[3]); w.z = pk_bf16(h[4], h[5]); w.w = pk_bf16(h[6], h[7]);
;                     *(u32x4*)(basep + (size_t)(row0 + ai * HALF + m * 16) * 1024 + col0 + bj * HALF) = w;
.LBB0_1943:
	v_lshlrev_b64 v[44:45], 11, v[2:3]
	v_lshl_add_u64 v[44:45], v[124:125], 0, v[44:45]
	v_cvt_pk_bf16_f32 v48, v48, v49
	v_cvt_pk_bf16_f32 v49, v50, v51
	v_cvt_pk_bf16_f32 v51, v46, v47
	v_add_co_u32_e32 v46, vcc, 0x48000, v44
	v_cvt_pk_bf16_f32 v50, v52, v53
	s_nop 0
	v_addc_co_u32_e32 v47, vcc, 0, v45, vcc
	s_and_b64 vcc, exec, s[10:11]
	v_mul_f32_e32 v40, v40, v0
	global_store_dwordx4 v[46:47], v[48:51], off sc1
	s_cbranch_vccnz .LBB0_1945
	v_mul_f32_e32 v46, 0x3d372713, v40
	v_mul_f32_e32 v46, v40, v46
	v_fma_f32 v46, v40, v46, v40
	v_mul_f32_e32 v46, 0x3fcc422a, v46
	v_mul_f32_e32 v46, 0xbfb8aa3b, v46
	v_exp_f32_e32 v46, v46
	s_nop 0
	v_add_f32_e32 v46, 1.0, v46
	v_rcp_f32_e32 v46, v46
	s_nop 0
	v_mul_f32_e32 v40, v40, v46

; #define PG8_LAS __attribute__((address_space(3)))
; __device__ __forceinline__ unsigned pk_bf16(float lo, float hi) { typedef __bf16 b2_t __attribute__((ext_vector_type(2))); f32x2 v = {lo, hi}; b2_t b = __builtin_convertvector(v, b2_t); return __builtin_bit_cast(unsigned, b); }
; __device__ __forceinline__ float fast_sigmoid(float v) { return __builtin_amdgcn_rcpf(1.0f + __builtin_amdgcn_exp2f(-1.44269504089f * v)); }
;     __device__ __forceinline__ void operator()(const f32x4 (&acc)[2][2][4][2], const Unit& u, int wr, int wc, int fr, int fq, PG8_LAS unsigned char* lds, int wid) const {
;     ...
;                 const float rstd = __builtin_amdgcn_rsqf(*(const PG8_LAS float*)(lds + PRE_SLOT + wid * 512 + (m & 1) * 256 + (fr + 16 * ((ai * 4 + m) >> 1)) * 4) * (1.0f / 1024.0f) + 1e-6f);
; #pragma unroll
;                 for (int bj = 0; bj < 2; ++bj) {
;                     float h[8];
; #pragma unroll
;                     for (int n = 0; n < 2; ++n)
; #pragma unroll
;                         for (int j = 0; j < 4; ++j) { float v = acc[ai][bj][m][n][j] * rstd;
;                             if (act) { const float z = 1.5957691216f * (v + 0.044715f * v * v * v); v = v * fast_sigmoid(z); }
;                             h[4 * n + j] = v; }
;                     u32x4 w; w.x = pk_bf16(h[0], h[1]); w.y = pk_bf16(h[2], h[3]); w.z = pk_bf16(h[4], h[5]); w.w = pk_bf16(h[6], h[7]);
;                     *(u32x4*)(basep + (size_t)(row0 + ai * HALF + m * 16) * 1024 + col0 + bj * HALF) = w;
.LBB0_1959:
	ds_read_b32 v0, v154 offset:192
	v_lshl_add_u64 v[44:45], v[44:45], 0, s[20:21]
	v_cvt_pk_bf16_f32 v40, v40, v41
	v_cvt_pk_bf16_f32 v41, v42, v43
	v_cvt_pk_bf16_f32 v42, v36, v37
	s_waitcnt lgkmcnt(0)
	v_fmamk_f32 v0, v0, 0x3a800000, v148
	v_rsq_f32_e32 v0, v0
	v_cvt_pk_bf16_f32 v43, v38, v39
	s_and_b64 vcc, exec, s[10:11]
	global_store_dwordx4 v[44:45], v[40:43], off offset:256 sc1
	v_mul_f32_e32 v32, v32, v0
	s_cbranch_vccnz .LBB0_1961
	v_mul_f32_e32 v36, 0x3d372713, v32
	v_mul_f32_e32 v36, v32, v36
	v_fma_f32 v36, v32, v36, v32
	v_mul_f32_e32 v36, 0x3fcc422a, v36
	v_mul_f32_e32 v36, 0xbfb8aa3b, v36
	v_exp_f32_e32 v36, v36
	s_nop 0
	v_add_f32_e32 v36, 1.0, v36
	v_rcp_f32_e32 v36, v36
	s_nop 0
	v_mul_f32_e32 v32, v32, v36

; #define PG8_LAS __attribute__((address_space(3)))
; __device__ __forceinline__ unsigned pk_bf16(float lo, float hi) { typedef __bf16 b2_t __attribute__((ext_vector_type(2))); f32x2 v = {lo, hi}; b2_t b = __builtin_convertvector(v, b2_t); return __builtin_bit_cast(unsigned, b); }
; __device__ __forceinline__ float fast_sigmoid(float v) { return __builtin_amdgcn_rcpf(1.0f + __builtin_amdgcn_exp2f(-1.44269504089f * v)); }
;     __device__ __forceinline__ void operator()(const f32x4 (&acc)[2][2][4][2], const Unit& u, int wr, int wc, int fr, int fq, PG8_LAS unsigned char* lds, int wid) const {
;     ...
;                 const float rstd = __builtin_amdgcn_rsqf(*(const PG8_LAS float*)(lds + PRE_SLOT + wid * 512 + (m & 1) * 256 + (fr + 16 * ((ai * 4 + m) >> 1)) * 4) * (1.0f / 1024.0f) + 1e-6f);
; #pragma unroll
;                 for (int bj = 0; bj < 2; ++bj) {
;                     float h[8];
; #pragma unroll
;                     for (int n = 0; n < 2; ++n)
; #pragma unroll
;                         for (int j = 0; j < 4; ++j) { float v = acc[ai][bj][m][n][j] * rstd;
;                             if (act) { const float z = 1.5957691216f * (v + 0.044715f * v * v * v); v = v * fast_sigmoid(z); }
;                             h[4 * n + j] = v; }
;                     u32x4 w; w.x = pk_bf16(h[0], h[1]); w.y = pk_bf16(h[2], h[3]); w.z = pk_bf16(h[4], h[5]); w.w = pk_bf16(h[6], h[7]);
;                     *(u32x4*)(basep + (size_t)(row0 + ai * HALF + m * 16) * 1024 + col0 + bj * HALF) = w;
.LBB0_1975:
	v_lshlrev_b64 v[28:29], 11, v[2:3]
	v_lshl_add_u64 v[28:29], v[124:125], 0, v[28:29]
	v_cvt_pk_bf16_f32 v32, v32, v33
	v_cvt_pk_bf16_f32 v33, v34, v35
	v_cvt_pk_bf16_f32 v35, v30, v31
	v_add_co_u32_e32 v30, vcc, 0x50000, v28
	v_cvt_pk_bf16_f32 v34, v36, v37
	s_nop 0
	v_addc_co_u32_e32 v31, vcc, 0, v29, vcc
	s_and_b64 vcc, exec, s[10:11]
	v_mul_f32_e32 v24, v24, v0
	global_store_dwordx4 v[30:31], v[32:35], off sc1
	s_cbranch_vccnz .LBB0_1977
	v_mul_f32_e32 v30, 0x3d372713, v24
	v_mul_f32_e32 v30, v24, v30
	v_fma_f32 v30, v24, v30, v24
	v_mul_f32_e32 v30, 0x3fcc422a, v30
	v_mul_f32_e32 v30, 0xbfb8aa3b, v30
	v_exp_f32_e32 v30, v30
	s_nop 0
	v_add_f32_e32 v30, 1.0, v30
	v_rcp_f32_e32 v30, v30
	s_nop 0
	v_mul_f32_e32 v24, v24, v30

; #define PG8_LAS __attribute__((address_space(3)))
; __device__ __forceinline__ unsigned pk_bf16(float lo, float hi) { typedef __bf16 b2_t __attribute__((ext_vector_type(2))); f32x2 v = {lo, hi}; b2_t b = __builtin_convertvector(v, b2_t); return __builtin_bit_cast(unsigned, b); }
; __device__ __forceinline__ float fast_sigmoid(float v) { return __builtin_amdgcn_rcpf(1.0f + __builtin_amdgcn_exp2f(-1.44269504089f * v)); }
;     __device__ __forceinline__ void operator()(const f32x4 (&acc)[2][2][4][2], const Unit& u, int wr, int wc, int fr, int fq, PG8_LAS unsigned char* lds, int wid) const {
;     ...
;                 const float rstd = __builtin_amdgcn_rsqf(*(const PG8_LAS float*)(lds + PRE_SLOT + wid * 512 + (m & 1) * 256 + (fr + 16 * ((ai * 4 + m) >> 1)) * 4) * (1.0f / 1024.0f) + 1e-6f);
; #pragma unroll
;                 for (int bj = 0; bj < 2; ++bj) {
;                     float h[8];
; #pragma unroll
;                     for (int n = 0; n < 2; ++n)
; #pragma unroll
;                         for (int j = 0; j < 4; ++j) { float v = acc[ai][bj][m][n][j] * rstd;
;                             if (act) { const float z = 1.5957691216f * (v + 0.044715f * v * v * v); v = v * fast_sigmoid(z); }
;                             h[4 * n + j] = v; }
;                     u32x4 w; w.x = pk_bf16(h[0], h[1]); w.y = pk_bf16(h[2], h[3]); w.z = pk_bf16(h[4], h[5]); w.w = pk_bf16(h[6], h[7]);
;                     *(u32x4*)(basep + (size_t)(row0 + ai * HALF + m * 16) * 1024 + col0 + bj * HALF) = w;
.LBB0_1991:
	ds_read_b32 v0, v154 offset:448
	v_lshl_add_u64 v[28:29], v[28:29], 0, s[22:23]
	v_cvt_pk_bf16_f32 v24, v24, v25
	v_cvt_pk_bf16_f32 v25, v26, v27
	v_cvt_pk_bf16_f32 v26, v20, v21
	s_waitcnt lgkmcnt(0)
	v_fmamk_f32 v0, v0, 0x3a800000, v148
	v_rsq_f32_e32 v0, v0
	v_cvt_pk_bf16_f32 v27, v22, v23
	s_and_b64 vcc, exec, s[10:11]
	global_store_dwordx4 v[28:29], v[24:27], off offset:256 sc1
	v_mul_f32_e32 v16, v16, v0
	s_cbranch_vccnz .LBB0_1993
	v_mul_f32_e32 v20, 0x3d372713, v16
	v_mul_f32_e32 v20, v16, v20
	v_fma_f32 v20, v16, v20, v16
	v_mul_f32_e32 v20, 0x3fcc422a, v20
	v_mul_f32_e32 v20, 0xbfb8aa3b, v20
	v_exp_f32_e32 v20, v20
	s_nop 0
	v_add_f32_e32 v20, 1.0, v20
	v_rcp_f32_e32 v20, v20
	s_nop 0
	v_mul_f32_e32 v16, v16, v20

; #define PG8_LAS __attribute__((address_space(3)))
; __device__ __forceinline__ unsigned pk_bf16(float lo, float hi) { typedef __bf16 b2_t __attribute__((ext_vector_type(2))); f32x2 v = {lo, hi}; b2_t b = __builtin_convertvector(v, b2_t); return __builtin_bit_cast(unsigned, b); }
; __device__ __forceinline__ float fast_sigmoid(float v) { return __builtin_amdgcn_rcpf(1.0f + __builtin_amdgcn_exp2f(-1.44269504089f * v)); }
;     __device__ __forceinline__ void operator()(const f32x4 (&acc)[2][2][4][2], const Unit& u, int wr, int wc, int fr, int fq, PG8_LAS unsigned char* lds, int wid) const {
;     ...
;                 const float rstd = __builtin_amdgcn_rsqf(*(const PG8_LAS float*)(lds + PRE_SLOT + wid * 512 + (m & 1) * 256 + (fr + 16 * ((ai * 4 + m) >> 1)) * 4) * (1.0f / 1024.0f) + 1e-6f);
; #pragma unroll
;                 for (int bj = 0; bj < 2; ++bj) {
;                     float h[8];
; #pragma unroll
;                     for (int n = 0; n < 2; ++n)
; #pragma unroll
;                         for (int j = 0; j < 4; ++j) { float v = acc[ai][bj][m][n][j] * rstd;
;                             if (act) { const float z = 1.5957691216f * (v + 0.044715f * v * v * v); v = v * fast_sigmoid(z); }
;                             h[4 * n + j] = v; }
;                     u32x4 w; w.x = pk_bf16(h[0], h[1]); w.y = pk_bf16(h[2], h[3]); w.z = pk_bf16(h[4], h[5]); w.w = pk_bf16(h[6], h[7]);
;                     *(u32x4*)(basep + (size_t)(row0 + ai * HALF + m * 16) * 1024 + col0 + bj * HALF) = w;
.LBB0_2007:
	v_lshlrev_b64 v[2:3], 11, v[2:3]
	v_lshl_add_u64 v[2:3], v[124:125], 0, v[2:3]
	v_cvt_pk_bf16_f32 v16, v16, v17
	v_cvt_pk_bf16_f32 v17, v18, v19
	v_cvt_pk_bf16_f32 v18, v12, v13
	v_add_co_u32_e32 v12, vcc, 0x58000, v2
	v_cvt_pk_bf16_f32 v19, v14, v15
	s_nop 0
	v_addc_co_u32_e32 v13, vcc, 0, v3, vcc
	s_and_b64 vcc, exec, s[10:11]
	v_mul_f32_e32 v8, v8, v0
	global_store_dwordx4 v[12:13], v[16:19], off sc1
	s_cbranch_vccnz .LBB0_2009
	v_mul_f32_e32 v12, 0x3d372713, v8
	v_mul_f32_e32 v12, v8, v12
	v_fma_f32 v12, v8, v12, v8
	v_mul_f32_e32 v12, 0x3fcc422a, v12
	v_mul_f32_e32 v12, 0xbfb8aa3b, v12
	v_exp_f32_e32 v12, v12
	s_nop 0
	v_add_f32_e32 v12, 1.0, v12
	v_rcp_f32_e32 v12, v12
	s_nop 0
	v_mul_f32_e32 v8, v8, v12

; #define PG8_LAS __attribute__((address_space(3)))
; __device__ __forceinline__ unsigned pk_bf16(float lo, float hi) { typedef __bf16 b2_t __attribute__((ext_vector_type(2))); f32x2 v = {lo, hi}; b2_t b = __builtin_convertvector(v, b2_t); return __builtin_bit_cast(unsigned, b); }
; __device__ __forceinline__ float fast_sigmoid(float v) { return __builtin_amdgcn_rcpf(1.0f + __builtin_amdgcn_exp2f(-1.44269504089f * v)); }
; #define PG8_BAR __builtin_amdgcn_s_barrier()
;     __device__ __forceinline__ void operator()(const f32x4 (&acc)[2][2][4][2], const Unit& u, int wr, int wc, int fr, int fq, PG8_LAS unsigned char* lds, int wid) const {
;     ...
;                 const float rstd = __builtin_amdgcn_rsqf(*(const PG8_LAS float*)(lds + PRE_SLOT + wid * 512 + (m & 1) * 256 + (fr + 16 * ((ai * 4 + m) >> 1)) * 4) * (1.0f / 1024.0f) + 1e-6f);
; #pragma unroll
;                 for (int bj = 0; bj < 2; ++bj) {
;                     float h[8];
; #pragma unroll
;                     for (int n = 0; n < 2; ++n)
; #pragma unroll
;                         for (int j = 0; j < 4; ++j) { float v = acc[ai][bj][m][n][j] * rstd;
;                             if (act) { const float z = 1.5957691216f * (v + 0.044715f * v * v * v); v = v * fast_sigmoid(z); }
;                             h[4 * n + j] = v; }
;                     u32x4 w; w.x = pk_bf16(h[0], h[1]); w.y = pk_bf16(h[2], h[3]); w.z = pk_bf16(h[4], h[5]); w.w = pk_bf16(h[6], h[7]);
;                     *(u32x4*)(basep + (size_t)(row0 + ai * HALF + m * 16) * 1024 + col0 + bj * HALF) = w;
; template <class Epi, class Sched, bool ALIGN_EPI = false, bool SP2 = false>
; __device__ __forceinline__ void gemm_phase(PG8_LAS unsigned char* lds, const Gemm g, const Sched& S, const Epi& E, int wave_s) {
;     ...
;         if (!has_next) break;
; #pragma unroll
;         for (int a = 0; a < 2; ++a)
; #pragma unroll
;             for (int b = 0; b < 2; ++b)
; #pragma unroll
;                 for (int m = 0; m < 4; ++m)
; #pragma unroll
;                     for (int n = 0; n < 2; ++n) acc[a][b][m][n] = (f32x4){0.f, 0.f, 0.f, 0.f};
;         cur = nxt; cA = nA; cB = nB; ++ui;
;         if constexpr (ALIGN_EPI) { if (wr == 1) PG8_BAR; }
.LBB0_2023:
	v_lshl_add_u64 v[12:13], v[2:3], 0, s[24:25]
	v_cvt_pk_bf16_f32 v2, v8, v9
	v_cvt_pk_bf16_f32 v3, v10, v11
	v_cvt_pk_bf16_f32 v4, v4, v5
	v_cvt_pk_bf16_f32 v5, v6, v0
	s_andn2_b64 vcc, exec, s[8:9]
	s_mov_b64 s[8:9], -1
	global_store_dwordx4 v[12:13], v[2:5], off offset:256 sc1
	s_cbranch_vccnz .LBB0_1756
	s_andn2_b64 vcc, exec, s[16:17]
	s_cbranch_vccnz .LBB0_1755
	s_barrier
	s_branch .LBB0_1755

; __device__ __forceinline__ unsigned pk_bf16(float lo, float hi) { typedef __bf16 b2_t __attribute__((ext_vector_type(2))); f32x2 v = {lo, hi}; b2_t b = __builtin_convertvector(v, b2_t); return __builtin_bit_cast(unsigned, b); }
; #define LAS __attribute__((address_space(3)))
; #define LDS_BARRIER() do { asm volatile("s_waitcnt lgkmcnt(0)" ::: "memory"); __builtin_amdgcn_s_barrier(); asm volatile("" ::: "memory"); } while (0)
; __device__ __forceinline__ void lru_phase(LAS unsigned char* lds, const bf16* XB, const bf16* Y, bf16* HY, const bf16* WRt, const bf16* WIt,
;         const float* convw, const float* convb, const float* br, const float* bi, const float* lam, unsigned long long* gran, int G, int bid, int wave_s) {
;     ...
;         {
;             float h = 0.f;
;             for (int kk = 0; kk < ch; ++kk) h = pA[kk * 64 + d] * h + pH[kk * 64 + d];
;             for (int s = 0; s < 7; ++s) { if (s < sg) h = segA[s * 64 + d] * h + segH[s * 64 + d]; }
; #pragma unroll
;             for (int i = 0; i < 16; ++i) { const int t = tb + i; h = av[i] * h + uv[i];
;                 const float yv_ = __uint_as_float((unsigned)yL[t * KP + d] << 16);
;                 xcB[t * KP + d] = (bf16)(pk_bf16(h * yv_, 0.f) & 0xffffu); }
;         }
;         LDS_BARRIER();
; #pragma unroll
;         for (int r = 0; r < 2; ++r) *(v4u*)(HY + (size_t)(b * SEQ + t0 + st + 64 * r) * D + c0 + cc) = *(const LAS v4u*)(xcB + (st + 64 * r) * KP + cc);
.LBB0_2103:
	s_or_b64 exec, exec, s[60:61]
	ds_read_u16 v0, v154
	v_fmac_f32_e32 v209, v207, v1
	v_fmac_f32_e32 v211, v208, v209
	v_fmac_f32_e32 v213, v210, v211
	v_fmac_f32_e32 v215, v212, v213
	s_waitcnt lgkmcnt(0)
	v_lshlrev_b32_e32 v0, 16, v0
	v_mul_f32_e32 v0, v209, v0
	v_cvt_pk_bf16_f32 v0, v0, s0
	ds_write_b16 v155, v0
	ds_read_u16 v0, v156
	v_fmac_f32_e32 v217, v214, v215
	v_fmac_f32_e32 v219, v216, v217
	v_fmac_f32_e32 v221, v218, v219
	v_fmac_f32_e32 v227, v220, v221
	s_waitcnt lgkmcnt(0)
	v_lshlrev_b32_e32 v0, 16, v0
	v_mul_f32_e32 v0, v211, v0
	v_cvt_pk_bf16_f32 v0, v0, s0
	ds_write_b16 v157, v0
	ds_read_u16 v0, v158
	v_fmac_f32_e32 v231, v225, v227
	v_fmac_f32_e32 v234, v230, v231
	v_fmac_f32_e32 v226, v233, v234
	v_fmac_f32_e32 v223, v224, v226
	s_waitcnt lgkmcnt(0)
	v_lshlrev_b32_e32 v0, 16, v0
	v_mul_f32_e32 v0, v213, v0
	v_cvt_pk_bf16_f32 v0, v0, s0
	ds_write_b16 v159, v0
	ds_read_u16 v0, v160
	v_fmac_f32_e32 v229, v222, v223
	v_fmac_f32_e32 v232, v228, v229
	v_fmac_f32_e32 v98, v30, v232
	s_and_b32 s60, s84, 0xffffff80
	s_waitcnt lgkmcnt(0)
	v_lshlrev_b32_e32 v0, 16, v0
	v_mul_f32_e32 v0, v215, v0
	v_cvt_pk_bf16_f32 v0, v0, s0
	ds_write_b16 v161, v0
	ds_read_u16 v0, v162
	s_lshl_b32 s61, s82, 11
	s_add_i32 s61, s61, s60
	s_lshl_b32 s6, s91, 1
	s_mov_b32 s7, s42
	s_waitcnt lgkmcnt(0)
	v_lshlrev_b32_e32 v0, 16, v0
	v_mul_f32_e32 v0, v217, v0
	v_cvt_pk_bf16_f32 v0, v0, s0
	ds_write_b16 v163, v0
	ds_read_u16 v0, v164
	v_fmac_f32_e32 v99, v31, v98
	s_mov_b32 s84, s93
	s_waitcnt lgkmcnt(0)
	v_lshlrev_b32_e32 v0, 16, v0
	v_mul_f32_e32 v0, v219, v0
	v_cvt_pk_bf16_f32 v0, v0, s0
	ds_write_b16 v165, v0
	ds_read_u16 v0, v166
	s_waitcnt lgkmcnt(0)
	v_lshlrev_b32_e32 v0, 16, v0
	v_mul_f32_e32 v0, v221, v0
	v_cvt_pk_bf16_f32 v0, v0, s0
	ds_write_b16 v167, v0
	ds_read_u16 v0, v168
	s_waitcnt lgkmcnt(0)
	v_lshlrev_b32_e32 v0, 16, v0
	v_mul_f32_e32 v0, v227, v0
	v_cvt_pk_bf16_f32 v0, v0, s0
	ds_write_b16 v169, v0
	ds_read_u16 v0, v170
	s_waitcnt lgkmcnt(0)
	v_lshlrev_b32_e32 v0, 16, v0
	v_mul_f32_e32 v0, v231, v0
	v_cvt_pk_bf16_f32 v0, v0, s0
	ds_write_b16 v171, v0
	ds_read_u16 v0, v172
	s_waitcnt lgkmcnt(0)
	v_lshlrev_b32_e32 v0, 16, v0
	v_mul_f32_e32 v0, v234, v0
	v_cvt_pk_bf16_f32 v0, v0, s0
	ds_write_b16 v173, v0
	ds_read_u16 v0, v175
	s_waitcnt lgkmcnt(0)
	v_lshlrev_b32_e32 v0, 16, v0
	v_mul_f32_e32 v0, v226, v0
	v_cvt_pk_bf16_f32 v0, v0, s0
	ds_write_b16 v176, v0
	ds_read_u16 v0, v177
	s_waitcnt lgkmcnt(0)
	v_lshlrev_b32_e32 v0, 16, v0
	v_mul_f32_e32 v0, v223, v0
	v_cvt_pk_bf16_f32 v0, v0, s0
	ds_write_b16 v178, v0
	ds_read_u16 v0, v179
	s_waitcnt lgkmcnt(0)
	v_lshlrev_b32_e32 v0, 16, v0
	v_mul_f32_e32 v0, v229, v0
	v_cvt_pk_bf16_f32 v0, v0, s0
	ds_write_b16 v180, v0
	ds_read_u16 v2, v181
	v_lshl_add_u64 v[0:1], v[80:81], 0, s[6:7]
	s_waitcnt lgkmcnt(0)
	v_lshlrev_b32_e32 v2, 16, v2
	v_mul_f32_e32 v2, v232, v2
	v_cvt_pk_bf16_f32 v2, v2, s0
	ds_write_b16 v182, v2
	ds_read_u16 v4, v183
	v_add_u32_e32 v2, s61, v100
	v_ashrrev_i32_e32 v3, 31, v2
	v_lshlrev_b64 v[2:3], 11, v[2:3]
	v_lshl_add_u64 v[8:9], v[0:1], 0, v[2:3]
	s_waitcnt lgkmcnt(0)
	v_lshlrev_b32_e32 v4, 16, v4
	v_mul_f32_e32 v4, v98, v4
	v_cvt_pk_bf16_f32 v4, v4, s0
	ds_write_b16 v184, v4
	ds_read_u16 v4, v185
	v_add_co_u32_e32 v10, vcc, 0x20000, v8
	s_waitcnt lgkmcnt(0)
	v_lshlrev_b32_e32 v0, 16, v4
	v_mul_f32_e32 v0, v99, v0
	v_cvt_pk_bf16_f32 v0, v0, s0
	ds_write_b16 v186, v0
	s_waitcnt lgkmcnt(0)
	s_barrier
	ds_read_b128 v[0:3], v206
	ds_read_b128 v[4:7], v117
	v_addc_co_u32_e32 v11, vcc, 0, v9, vcc
	s_andn2_b64 vcc, exec, s[58:59]
	s_waitcnt lgkmcnt(1)
	global_store_dwordx4 v[8:9], v[0:3], off sc1
	s_waitcnt lgkmcnt(0)
	global_store_dwordx4 v[10:11], v[4:7], off sc1
	s_cbranch_vccz .LBB0_2229

; __device__ __forceinline__ int lane_id_() { int l; asm volatile("v_mbcnt_lo_u32_b32 %0, -1, 0\n\tv_mbcnt_hi_u32_b32 %0, -1, %0" : "=v"(l)); return l; }
; #define PG8_WAIT_V(n) asm volatile("s_waitcnt vmcnt(" #n ")" ::: "memory")
; #define PG8_BAR __builtin_amdgcn_s_barrier()
; __device__ __forceinline__ unsigned xb_ld(unsigned* p)              { return __hip_atomic_load(p, __ATOMIC_RELAXED, __HIP_MEMORY_SCOPE_AGENT); }
; __device__ __forceinline__ unsigned xb_add(unsigned* p, unsigned v) { return __hip_atomic_fetch_add(p, v, __ATOMIC_RELAXED, __HIP_MEMORY_SCOPE_AGENT); }
; #define XB_SPIN(cond, bar) do { unsigned _sp = 0; while (cond) { __builtin_amdgcn_s_sleep(1); \
;     if ((++_sp & 255u) == 0u) { if (xb_ld(&(bar)[XB_TMO])) break; if (_sp > XB_SPIN_CAP) { atomicAdd(&(bar)[XB_TMO], 1u); break; } } } } while (0)
; template <class Epi, class Sched, bool ALIGN_EPI = false, bool SP2 = false>
; __device__ __forceinline__ void gemm_phase(PG8_LAS unsigned char* lds, const Gemm g, const Sched& S, const Epi& E, int wave_s) {
;     ...
;     PG8_WAIT_V(0);
;     if constexpr (!ALIGN_EPI) { if (wr == 0) PG8_BAR; }
;     PG8_BAR;
; __device__ __forceinline__ void xcd_barrier(const XcdBarrier& b, int wave_s) {
;     asm volatile("s_waitcnt vmcnt(0)" ::: "memory");
;     __syncthreads();
;     if (wave_s == 0 && lane_id_() == 0) {
;         unsigned* bar = b.bar;
;         __builtin_amdgcn_s_waitcnt(0);
;         unsigned nloc = b.st[0], nx = b.st[1];
;         if (nloc == 0u) { xcd_barrier_complete(bar, b.x, nloc, nx); b.st[0] = nloc; b.st[1] = nx; }
;         const unsigned old = xb_add(&bar[XB_XSUB(b.x)], 1u);
;         const unsigned gen = old / nloc;
;         if (old + 1u == (gen + 1u) * nloc) {
;             __builtin_amdgcn_fence(__ATOMIC_RELEASE, "agent");
;             asm volatile("s_waitcnt vmcnt(0)" ::: "memory");
;             const unsigned og = xb_add(&bar[XB_TOP], 1u);
;             const unsigned tg = og / nx;
;             if (og + 1u == (tg + 1u) * nx) xb_add(&bar[XB_TOPGEN], 1u);
;             else XB_SPIN(xb_ld(&bar[XB_TOPGEN]) == tg, bar);
;             __builtin_amdgcn_fence(__ATOMIC_ACQUIRE, "agent");
;             xb_add(&bar[XB_XGEN(b.x)], 1u);
.LBB0_2327:
	s_waitcnt vmcnt(0)
	s_and_b64 vcc, exec, s[2:3]
	s_waitcnt lgkmcnt(0)
	s_barrier
	s_cbranch_vccnz .LBB0_2381
	v_mbcnt_lo_u32_b32 v0, -1, 0
	v_mbcnt_hi_u32_b32 v0, -1, v0
	s_nop 0
	v_cmp_eq_u32_e32 vcc, 0, v0
	s_and_saveexec_b64 s[8:9], vcc
	s_cbranch_execz .LBB0_2380
	s_cmp_eq_u32 s101, 1
	s_cbranch_scc0 .Lglob_S13
	s_and_b32 s98, s33, 7
	s_lshl_b32 s99, s98, 2
	s_addk_i32 s99, 0x4800
	v_mov_b32_e32 v3, s99
	s_lshl_b32 s98, s98, 8
	s_addk_i32 s98, 0x4000
	v_mov_b32_e32 v0, s98
	v_mov_b32_e32 v1, 1
	global_atomic_add v2, v0, v1, s[44:45] sc0
	buffer_inv sc1
	s_waitcnt vmcnt(1)
	v_readfirstlane_b32 s98, v2
	s_nop 3
	s_add_u32 s99, s98, 1
	s_and_b32 s99, s99, 31
	s_lshr_b32 s98, s98, 5
	s_cmp_eq_u32 s99, 0
	s_cbranch_scc0 .Llw_S13
	global_atomic_add v3, v1, s[44:45]

; __device__ __forceinline__ int lane_id_() { int l; asm volatile("v_mbcnt_lo_u32_b32 %0, -1, 0\n\tv_mbcnt_hi_u32_b32 %0, -1, %0" : "=v"(l)); return l; }
; #define PG8_WAIT_V(n) asm volatile("s_waitcnt vmcnt(" #n ")" ::: "memory")
; #define PG8_BAR __builtin_amdgcn_s_barrier()
; __device__ __forceinline__ unsigned xb_ld(unsigned* p)              { return __hip_atomic_load(p, __ATOMIC_RELAXED, __HIP_MEMORY_SCOPE_AGENT); }
; __device__ __forceinline__ unsigned xb_add(unsigned* p, unsigned v) { return __hip_atomic_fetch_add(p, v, __ATOMIC_RELAXED, __HIP_MEMORY_SCOPE_AGENT); }
; #define XB_SPIN(cond, bar) do { unsigned _sp = 0; while (cond) { __builtin_amdgcn_s_sleep(1); \
;     if ((++_sp & 255u) == 0u) { if (xb_ld(&(bar)[XB_TMO])) break; if (_sp > XB_SPIN_CAP) { atomicAdd(&(bar)[XB_TMO], 1u); break; } } } } while (0)
; template <class Epi, class Sched, bool ALIGN_EPI = false, bool SP2 = false>
; __device__ __forceinline__ void gemm_phase(PG8_LAS unsigned char* lds, const Gemm g, const Sched& S, const Epi& E, int wave_s) {
;     ...
;     PG8_WAIT_V(0);
;     if constexpr (!ALIGN_EPI) { if (wr == 0) PG8_BAR; }
;     PG8_BAR;
; __device__ __forceinline__ void xcd_barrier(const XcdBarrier& b, int wave_s) {
;     asm volatile("s_waitcnt vmcnt(0)" ::: "memory");
;     __syncthreads();
;     if (wave_s == 0 && lane_id_() == 0) {
;         unsigned* bar = b.bar;
;         __builtin_amdgcn_s_waitcnt(0);
;         unsigned nloc = b.st[0], nx = b.st[1];
;         if (nloc == 0u) { xcd_barrier_complete(bar, b.x, nloc, nx); b.st[0] = nloc; b.st[1] = nx; }
;         const unsigned old = xb_add(&bar[XB_XSUB(b.x)], 1u);
;         const unsigned gen = old / nloc;
;         if (old + 1u == (gen + 1u) * nloc) {
;             __builtin_amdgcn_fence(__ATOMIC_RELEASE, "agent");
;             asm volatile("s_waitcnt vmcnt(0)" ::: "memory");
;             const unsigned og = xb_add(&bar[XB_TOP], 1u);
;             const unsigned tg = og / nx;
;             if (og + 1u == (tg + 1u) * nx) xb_add(&bar[XB_TOPGEN], 1u);
;             else XB_SPIN(xb_ld(&bar[XB_TOPGEN]) == tg, bar);
;             __builtin_amdgcn_fence(__ATOMIC_ACQUIRE, "agent");
;             xb_add(&bar[XB_XGEN(b.x)], 1u);
.LBB0_2397:
	s_waitcnt vmcnt(0)
	s_and_b64 vcc, exec, s[2:3]
	s_waitcnt vmcnt(0)
	s_barrier
	s_cbranch_vccnz .LBB0_2451
	v_mbcnt_lo_u32_b32 v0, -1, 0
	v_mbcnt_hi_u32_b32 v0, -1, v0
	s_nop 0
	v_cmp_eq_u32_e32 vcc, 0, v0
	s_and_saveexec_b64 s[2:3], vcc
	s_cbranch_execz .LBB0_2450
	s_cmp_eq_u32 s101, 1
	s_cbranch_scc0 .Lglob_S14
	s_and_b32 s98, s33, 7
	s_lshl_b32 s99, s98, 2
	s_addk_i32 s99, 0x4800
	v_mov_b32_e32 v3, s99
	s_lshl_b32 s98, s98, 8
	s_addk_i32 s98, 0x4000
	v_mov_b32_e32 v0, s98
	v_mov_b32_e32 v1, 1
	global_atomic_add v2, v0, v1, s[44:45] sc0
	buffer_inv sc1
	s_waitcnt vmcnt(1)
	v_readfirstlane_b32 s98, v2
	s_nop 3
	s_add_u32 s99, s98, 1
	s_and_b32 s99, s99, 31
	s_lshr_b32 s98, s98, 5
	s_cmp_eq_u32 s99, 0
	s_cbranch_scc0 .Llw_S14
	global_atomic_add v3, v1, s[44:45]
	s_branch .Lla_S14
